# drop the nt hint on producer stores that the next GEMM phase reads as A (gate output, post0/norm0 H) so they stay in L2/MALL
# speedup vs baseline: 1.0152x; 1.0152x over previous
.LBB0_40:
	global_load_dwordx4 v[48:51], v[36:37], off offset:-2048 nt
	global_load_dwordx4 v[14:17], v[36:37], off offset:-1024 nt
	s_waitcnt lgkmcnt(0)
	global_load_dwordx4 v[6:9], v[36:37], off nt
	global_load_dwordx4 v[2:5], v[36:37], off offset:1024 nt
	s_add_i32 s36, s82, s27
	s_cmp_lt_i32 s36, 0x8000
	s_cselect_b32 s38, s36, s27
	s_ashr_i32 s37, s27, 31
	s_lshr_b32 s37, s37, 19
	s_add_i32 s37, s27, s37
	s_ashr_i32 s37, s37, 13
	s_mul_i32 s40, s37, 0xc00
	s_ashr_i32 s39, s38, 31
	s_ashr_i32 s41, s40, 31
	s_lshl_b64 s[38:39], s[38:39], 12
	s_lshl_b64 s[40:41], s[40:41], 2
	s_add_u32 s40, s34, s40
	s_addc_u32 s41, s35, s41
	v_lshl_add_u64 v[64:65], v[30:31], 2, s[40:41]
	v_add_co_u32_e32 v10, vcc, s3, v64
	v_lshl_add_u64 v[66:67], s[12:13], 0, v[38:39]
	s_nop 0
	v_addc_co_u32_e32 v11, vcc, 0, v65, vcc
	global_load_dwordx4 v[52:55], v[10:11], off
	global_load_dwordx4 v[56:59], v[34:35], off
	global_load_dwordx4 v[60:63], v[64:65], off
	s_cmpk_gt_i32 s36, 0x7fff
	s_waitcnt vmcnt(6)
	v_mov_b32_e32 v12, v49
	s_waitcnt vmcnt(5)
	v_mov_b32_e32 v13, v15
	v_mov_b32_e32 v10, v48
	v_mov_b32_e32 v11, v14
	s_waitcnt vmcnt(4)
	v_mov_b32_e32 v24, v7
	s_waitcnt vmcnt(3)
	v_mov_b32_e32 v25, v3
	v_pk_mul_f32 v[12:13], v[12:13], v[12:13]
	v_mov_b32_e32 v18, v50
	v_mov_b32_e32 v19, v16
	v_mov_b32_e32 v22, v6
	v_mov_b32_e32 v23, v2
	v_pk_mul_f32 v[24:25], v[24:25], v[24:25]
	v_pk_fma_f32 v[10:11], v[10:11], v[10:11], v[12:13]
	v_mov_b32_e32 v20, v51
	v_mov_b32_e32 v21, v17
	v_mov_b32_e32 v26, v8
	v_mov_b32_e32 v27, v4
	v_pk_fma_f32 v[12:13], v[22:23], v[22:23], v[24:25]
	v_pk_fma_f32 v[10:11], v[18:19], v[18:19], v[10:11]
	v_mov_b32_e32 v28, v9
	v_mov_b32_e32 v29, v5
	v_pk_fma_f32 v[12:13], v[26:27], v[26:27], v[12:13]
	v_pk_fma_f32 v[10:11], v[20:21], v[20:21], v[10:11]
	v_pk_fma_f32 v[12:13], v[28:29], v[28:29], v[12:13]
	v_add_f32_e32 v10, v10, v11
	v_add_f32_e32 v10, v10, v12
	v_add_f32_e32 v10, v10, v13
	ds_bpermute_b32 v11, v40, v10
	s_waitcnt vmcnt(2)
	v_pk_add_f32 v[52:53], v[52:53], 1.0 op_sel_hi:[1,0]
	v_pk_add_f32 v[54:55], v[54:55], 1.0 op_sel_hi:[1,0]
	s_waitcnt lgkmcnt(0)
	v_add_f32_e32 v10, v10, v11
	ds_bpermute_b32 v11, v41, v10
	s_waitcnt lgkmcnt(0)
	v_add_f32_e32 v10, v10, v11
	ds_bpermute_b32 v11, v42, v10
	s_waitcnt lgkmcnt(0)
	v_add_f32_e32 v10, v10, v11
	ds_bpermute_b32 v11, v43, v10
	s_waitcnt lgkmcnt(0)
	v_add_f32_e32 v12, v10, v11
	ds_bpermute_b32 v13, v44, v12
	v_lshl_add_u64 v[10:11], v[32:33], 0, s[38:39]
	s_waitcnt lgkmcnt(0)
	v_add_f32_e32 v47, v12, v13
	ds_bpermute_b32 v68, v45, v47
	global_load_dwordx4 v[26:29], v[10:11], off nt
	global_load_dwordx4 v[22:25], v[10:11], off offset:1024 nt
	global_load_dwordx4 v[18:21], v[10:11], off offset:2048 nt
	s_nop 0
	global_load_dwordx4 v[10:13], v[10:11], off offset:3072 nt
	s_waitcnt lgkmcnt(0)
	v_add_f32_e32 v47, v47, v68
	v_fmamk_f32 v47, v47, 0x3a800000, v46
	v_mul_f32_e32 v68, 0x4b800000, v47
	v_cmp_gt_f32_e32 vcc, s1, v47
	s_nop 1
	v_cndmask_b32_e32 v47, v47, v68, vcc
	v_rsq_f32_e32 v47, v47
	v_lshl_add_u64 v[68:69], v[64:65], 0, s[28:29]
	v_mul_f32_e32 v70, 0x45800000, v47
	v_cndmask_b32_e32 v70, v47, v70, vcc
	v_pk_mul_f32 v[48:49], v[48:49], v[70:71] op_sel_hi:[1,0]
	v_pk_mul_f32 v[50:51], v[50:51], v[70:71] op_sel_hi:[1,0]
	s_waitcnt vmcnt(5)
	v_pk_mul_f32 v[48:49], v[56:57], v[48:49]
	v_pk_mul_f32 v[50:51], v[58:59], v[50:51]
	s_waitcnt vmcnt(4)
	v_pk_fma_f32 v[48:49], v[48:49], v[52:53], v[60:61]
	v_pk_fma_f32 v[50:51], v[50:51], v[54:55], v[62:63]
	v_cvt_pk_bf16_f32 v48, v48, v49
	v_cvt_pk_bf16_f32 v49, v50, v51
	global_store_dwordx2 v[66:67], v[48:49], off
	global_load_dwordx4 v[48:51], v[34:35], off offset:1024
	s_nop 0
	global_load_dwordx4 v[52:55], v[68:69], off offset:1024
	global_load_dwordx4 v[56:59], v[64:65], off offset:1024
	v_pk_mul_f32 v[14:15], v[14:15], v[70:71] op_sel_hi:[1,0]
	v_pk_mul_f32 v[16:17], v[16:17], v[70:71] op_sel_hi:[1,0]
	v_pk_mul_f32 v[6:7], v[6:7], v[70:71] op_sel_hi:[1,0]
	v_pk_mul_f32 v[8:9], v[8:9], v[70:71] op_sel_hi:[1,0]
	v_pk_mul_f32 v[2:3], v[2:3], v[70:71] op_sel_hi:[1,0]
	v_pk_mul_f32 v[4:5], v[4:5], v[70:71] op_sel_hi:[1,0]
	s_waitcnt vmcnt(2)
	v_pk_mul_f32 v[14:15], v[14:15], v[48:49]
	s_waitcnt vmcnt(1)
	v_pk_add_f32 v[48:49], v[52:53], 1.0 op_sel_hi:[1,0]
	v_pk_mul_f32 v[16:17], v[16:17], v[50:51]
	v_pk_add_f32 v[50:51], v[54:55], 1.0 op_sel_hi:[1,0]
	s_waitcnt vmcnt(0)
	v_pk_fma_f32 v[14:15], v[14:15], v[48:49], v[56:57]
	v_pk_fma_f32 v[16:17], v[16:17], v[50:51], v[58:59]
	v_cvt_pk_bf16_f32 v14, v14, v15
	v_cvt_pk_bf16_f32 v15, v16, v17
	global_store_dwordx2 v[66:67], v[14:15], off offset:512
	global_load_dwordx4 v[14:17], v[34:35], off offset:2048
	s_nop 0
	global_load_dwordx4 v[48:51], v[68:69], off offset:2048
	global_load_dwordx4 v[52:55], v[64:65], off offset:2048
	s_waitcnt vmcnt(2)
	v_pk_mul_f32 v[6:7], v[6:7], v[14:15]
	s_waitcnt vmcnt(1)
	v_pk_add_f32 v[14:15], v[48:49], 1.0 op_sel_hi:[1,0]
	v_pk_mul_f32 v[8:9], v[8:9], v[16:17]
	v_pk_add_f32 v[16:17], v[50:51], 1.0 op_sel_hi:[1,0]
	s_waitcnt vmcnt(0)
	v_pk_fma_f32 v[6:7], v[6:7], v[14:15], v[52:53]
	v_pk_fma_f32 v[8:9], v[8:9], v[16:17], v[54:55]
	v_cvt_pk_bf16_f32 v6, v6, v7
	v_cvt_pk_bf16_f32 v7, v8, v9
	global_store_dwordx2 v[66:67], v[6:7], off offset:1024
	global_load_dwordx4 v[14:17], v[34:35], off offset:3072
	global_load_dwordx4 v[48:51], v[68:69], off offset:3072
	global_load_dwordx4 v[52:55], v[64:65], off offset:3072
	v_mul_f32_e32 v6, v27, v27
	v_mul_f32_e32 v7, v23, v23
	v_mul_f32_e32 v8, v19, v19
	v_fmac_f32_e32 v6, v26, v26
	v_fmac_f32_e32 v7, v22, v22
	v_mul_f32_e32 v9, v11, v11
	v_fmac_f32_e32 v8, v18, v18
	v_fmac_f32_e32 v6, v28, v28
	v_fmac_f32_e32 v7, v24, v24
	v_fmac_f32_e32 v9, v10, v10
	v_fmac_f32_e32 v8, v20, v20
	v_fmac_f32_e32 v6, v29, v29
	v_fmac_f32_e32 v7, v25, v25
	v_fmac_f32_e32 v9, v12, v12
	v_fmac_f32_e32 v8, v21, v21
	v_add_f32_e32 v6, v6, v7
	v_fmac_f32_e32 v9, v13, v13
	v_add_f32_e32 v6, v6, v8
	v_add_f32_e32 v6, v6, v9
	ds_bpermute_b32 v7, v40, v6
	s_waitcnt lgkmcnt(0)
	v_add_f32_e32 v6, v6, v7
	ds_bpermute_b32 v7, v41, v6
	s_waitcnt lgkmcnt(0)
	v_add_f32_e32 v6, v6, v7
	ds_bpermute_b32 v7, v42, v6
	s_waitcnt lgkmcnt(0)
	v_add_f32_e32 v6, v6, v7
	ds_bpermute_b32 v7, v43, v6
	s_waitcnt lgkmcnt(0)
	v_add_f32_e32 v6, v6, v7
	ds_bpermute_b32 v7, v44, v6
	s_waitcnt lgkmcnt(0)
	v_add_f32_e32 v6, v6, v7
	ds_bpermute_b32 v7, v45, v6
	s_waitcnt vmcnt(2)
	v_pk_mul_f32 v[2:3], v[2:3], v[14:15]
	s_waitcnt vmcnt(1)
	v_pk_add_f32 v[8:9], v[48:49], 1.0 op_sel_hi:[1,0]
	v_pk_mul_f32 v[4:5], v[4:5], v[16:17]
	v_pk_add_f32 v[14:15], v[50:51], 1.0 op_sel_hi:[1,0]
	s_waitcnt vmcnt(0)
	v_pk_fma_f32 v[2:3], v[2:3], v[8:9], v[52:53]
	v_pk_fma_f32 v[4:5], v[4:5], v[14:15], v[54:55]
	v_cvt_pk_bf16_f32 v2, v2, v3
	v_cvt_pk_bf16_f32 v3, v4, v5
	global_store_dwordx2 v[66:67], v[2:3], off offset:1536
	s_cbranch_scc1 .LBB0_39
	s_ashr_i32 s37, s36, 31
	s_lshr_b32 s37, s37, 19
	s_add_i32 s36, s36, s37
	s_ashr_i32 s36, s36, 13
	s_mulk_i32 s36, 0xc00
	s_ashr_i32 s37, s36, 31
	s_lshl_b64 s[36:37], s[36:37], 2
	s_add_u32 s36, s34, s36
	s_addc_u32 s37, s35, s37
	v_lshl_add_u64 v[52:53], v[30:31], 2, s[36:37]
	v_add_co_u32_e32 v8, vcc, s3, v52
	global_load_dwordx4 v[2:5], v[34:35], off
	s_nop 0
	v_addc_co_u32_e32 v9, vcc, 0, v53, vcc
	global_load_dwordx4 v[14:17], v[8:9], off
	global_load_dwordx4 v[48:51], v[52:53], off
	s_waitcnt lgkmcnt(0)
	v_add_f32_e32 v6, v6, v7
	v_fmamk_f32 v6, v6, 0x3a800000, v46
	v_mul_f32_e32 v7, 0x4b800000, v6
	v_cmp_gt_f32_e32 vcc, s1, v6
	v_lshl_add_u64 v[54:55], s[8:9], 0, v[38:39]
	v_lshl_add_u64 v[58:59], v[52:53], 0, s[28:29]
	v_cndmask_b32_e32 v6, v6, v7, vcc
	v_rsq_f32_e32 v6, v6
	s_nop 0
	v_mul_f32_e32 v7, 0x45800000, v6
	v_cndmask_b32_e32 v56, v6, v7, vcc
	v_pk_mul_f32 v[6:7], v[26:27], v[56:57] op_sel_hi:[1,0]
	v_pk_mul_f32 v[8:9], v[28:29], v[56:57] op_sel_hi:[1,0]
	v_pk_mul_f32 v[22:23], v[22:23], v[56:57] op_sel_hi:[1,0]
	v_pk_mul_f32 v[24:25], v[24:25], v[56:57] op_sel_hi:[1,0]
	v_pk_mul_f32 v[18:19], v[18:19], v[56:57] op_sel_hi:[1,0]
	v_pk_mul_f32 v[20:21], v[20:21], v[56:57] op_sel_hi:[1,0]
	v_pk_mul_f32 v[10:11], v[10:11], v[56:57] op_sel_hi:[1,0]
	v_pk_mul_f32 v[12:13], v[12:13], v[56:57] op_sel_hi:[1,0]
	s_waitcnt vmcnt(2)
	v_pk_mul_f32 v[2:3], v[6:7], v[2:3]
	v_pk_mul_f32 v[4:5], v[8:9], v[4:5]
	s_waitcnt vmcnt(1)
	v_pk_add_f32 v[6:7], v[14:15], 1.0 op_sel_hi:[1,0]
	v_pk_add_f32 v[8:9], v[16:17], 1.0 op_sel_hi:[1,0]
	s_waitcnt vmcnt(0)
	v_pk_fma_f32 v[2:3], v[2:3], v[6:7], v[48:49]
	v_pk_fma_f32 v[4:5], v[4:5], v[8:9], v[50:51]
	v_cvt_pk_bf16_f32 v2, v2, v3
	v_cvt_pk_bf16_f32 v3, v4, v5
	global_store_dwordx2 v[54:55], v[2:3], off
	global_load_dwordx4 v[2:5], v[34:35], off offset:1024
	s_nop 0
	global_load_dwordx4 v[6:9], v[58:59], off offset:1024
	global_load_dwordx4 v[14:17], v[52:53], off offset:1024
	s_waitcnt vmcnt(2)
	v_pk_mul_f32 v[2:3], v[22:23], v[2:3]
	s_waitcnt vmcnt(1)
	v_pk_add_f32 v[6:7], v[6:7], 1.0 op_sel_hi:[1,0]
	v_pk_mul_f32 v[4:5], v[24:25], v[4:5]
	v_pk_add_f32 v[8:9], v[8:9], 1.0 op_sel_hi:[1,0]
	s_waitcnt vmcnt(0)
	v_pk_fma_f32 v[2:3], v[2:3], v[6:7], v[14:15]
	v_pk_fma_f32 v[4:5], v[4:5], v[8:9], v[16:17]
	v_cvt_pk_bf16_f32 v2, v2, v3
	v_cvt_pk_bf16_f32 v3, v4, v5
	global_store_dwordx2 v[54:55], v[2:3], off offset:512
	global_load_dwordx4 v[2:5], v[34:35], off offset:2048
	s_nop 0
	global_load_dwordx4 v[6:9], v[58:59], off offset:2048
	global_load_dwordx4 v[14:17], v[52:53], off offset:2048
	s_waitcnt vmcnt(2)
	v_pk_mul_f32 v[2:3], v[18:19], v[2:3]
	s_waitcnt vmcnt(1)
	v_pk_add_f32 v[6:7], v[6:7], 1.0 op_sel_hi:[1,0]
	v_pk_mul_f32 v[4:5], v[20:21], v[4:5]
	v_pk_add_f32 v[8:9], v[8:9], 1.0 op_sel_hi:[1,0]
	s_waitcnt vmcnt(0)
	v_pk_fma_f32 v[2:3], v[2:3], v[6:7], v[14:15]
	v_pk_fma_f32 v[4:5], v[4:5], v[8:9], v[16:17]
	v_cvt_pk_bf16_f32 v2, v2, v3
	v_cvt_pk_bf16_f32 v3, v4, v5
	global_store_dwordx2 v[54:55], v[2:3], off offset:1024
	global_load_dwordx4 v[2:5], v[34:35], off offset:3072
	s_nop 0
	global_load_dwordx4 v[6:9], v[58:59], off offset:3072
	global_load_dwordx4 v[14:17], v[52:53], off offset:3072
	s_waitcnt vmcnt(2)
	v_pk_mul_f32 v[2:3], v[10:11], v[2:3]
	s_waitcnt vmcnt(1)
	v_pk_add_f32 v[6:7], v[6:7], 1.0 op_sel_hi:[1,0]
	v_pk_mul_f32 v[4:5], v[12:13], v[4:5]
	v_pk_add_f32 v[8:9], v[8:9], 1.0 op_sel_hi:[1,0]
	s_waitcnt vmcnt(0)
	v_pk_fma_f32 v[2:3], v[2:3], v[6:7], v[14:15]
	v_pk_fma_f32 v[4:5], v[4:5], v[8:9], v[16:17]
	v_cvt_pk_bf16_f32 v2, v2, v3
	v_cvt_pk_bf16_f32 v3, v4, v5
	global_store_dwordx2 v[54:55], v[2:3], off offset:1536
	s_branch .LBB0_39

.Lpost0_loop:
	s_add_u32 s10, s10, 0x800000
	s_addc_u32 s11, s11, 0
	s_add_u32 s12, s12, 0x800000
	s_addc_u32 s13, s13, 0
	s_add_u32 s14, s14, 0x400000
	s_addc_u32 s15, s15, 0
	s_add_u32 s16, s16, 0x400000
	s_addc_u32 s17, s17, 0
	global_load_dwordx2 v[48:49], v211, s[10:11] nt
	global_load_dwordx2 v[50:51], v211, s[10:11] offset:512 nt
	global_load_dwordx2 v[52:53], v211, s[10:11] offset:1024 nt
	global_load_dwordx2 v[54:55], v211, s[10:11] offset:1536 nt
	global_load_dwordx4 v[64:67], v210, s[14:15] nt
	global_load_dwordx4 v[68:71], v210, s[14:15] offset:1024 nt
	global_load_dwordx4 v[72:75], v210, s[14:15] offset:2048 nt
	global_load_dwordx4 v[76:79], v210, s[14:15] offset:3072 nt
	global_load_dwordx2 v[56:57], v211, s[12:13] nt
	global_load_dwordx2 v[58:59], v211, s[12:13] offset:512 nt
	global_load_dwordx2 v[60:61], v211, s[12:13] offset:1024 nt
	global_load_dwordx2 v[62:63], v211, s[12:13] offset:1536 nt
	global_load_dwordx4 v[80:83], v210, s[16:17] nt
	global_load_dwordx4 v[84:87], v210, s[16:17] offset:1024 nt
	global_load_dwordx4 v[88:91], v210, s[16:17] offset:2048 nt
	global_load_dwordx4 v[92:95], v210, s[16:17] offset:3072 nt
	s_waitcnt vmcnt(40)
	v_lshlrev_b32_e32 v176, 16, v0
	v_and_b32_e32 v177, 0xffff0000, v0
	v_lshlrev_b32_e32 v178, 16, v1
	v_and_b32_e32 v179, 0xffff0000, v1
	v_lshlrev_b32_e32 v180, 16, v2
	v_and_b32_e32 v181, 0xffff0000, v2
	v_lshlrev_b32_e32 v182, 16, v3
	v_and_b32_e32 v183, 0xffff0000, v3
	v_lshlrev_b32_e32 v184, 16, v4
	v_and_b32_e32 v185, 0xffff0000, v4
	v_lshlrev_b32_e32 v186, 16, v5
	v_and_b32_e32 v187, 0xffff0000, v5
	v_lshlrev_b32_e32 v188, 16, v6
	v_and_b32_e32 v189, 0xffff0000, v6
	v_lshlrev_b32_e32 v190, 16, v7
	v_and_b32_e32 v191, 0xffff0000, v7
	v_mul_f32_e32 v192, v176, v176
	v_fmac_f32_e32 v192, v177, v177
	v_fmac_f32_e32 v192, v178, v178
	v_fmac_f32_e32 v192, v179, v179
	v_fmac_f32_e32 v192, v180, v180
	v_fmac_f32_e32 v192, v181, v181
	v_fmac_f32_e32 v192, v182, v182
	v_fmac_f32_e32 v192, v183, v183
	v_fmac_f32_e32 v192, v184, v184
	v_fmac_f32_e32 v192, v185, v185
	v_fmac_f32_e32 v192, v186, v186
	v_fmac_f32_e32 v192, v187, v187
	v_fmac_f32_e32 v192, v188, v188
	v_fmac_f32_e32 v192, v189, v189
	v_fmac_f32_e32 v192, v190, v190
	v_fmac_f32_e32 v192, v191, v191
	v_mul_f32_e32 v194, v112, v176
	v_mul_f32_e32 v195, v113, v177
	v_mul_f32_e32 v196, v114, v178
	v_mul_f32_e32 v197, v115, v179
	v_mul_f32_e32 v198, v116, v180
	v_mul_f32_e32 v199, v117, v181
	v_mul_f32_e32 v200, v118, v182
	v_mul_f32_e32 v201, v119, v183
	v_mul_f32_e32 v202, v120, v184
	v_mul_f32_e32 v203, v121, v185
	v_mul_f32_e32 v204, v122, v186
	v_mul_f32_e32 v205, v123, v187
	v_mul_f32_e32 v206, v124, v188
	v_mul_f32_e32 v207, v125, v189
	v_mul_f32_e32 v208, v126, v190
	v_mul_f32_e32 v209, v127, v191
	s_nop 1
	v_add_f32_dpp v193, v192, v192 quad_perm:[1,0,3,2] row_mask:0xf bank_mask:0xf
	s_nop 1
	v_add_f32_dpp v192, v193, v193 quad_perm:[2,3,0,1] row_mask:0xf bank_mask:0xf
	s_nop 1
	v_add_f32_dpp v193, v192, v192 row_half_mirror row_mask:0xf bank_mask:0xf
	s_nop 1
	v_add_f32_dpp v192, v193, v193 row_mirror row_mask:0xf bank_mask:0xf
	s_nop 0
	v_readlane_b32 s0, v192, 0
	v_readlane_b32 s1, v192, 16
	v_readlane_b32 s6, v192, 32
	v_readlane_b32 s7, v192, 48
	s_nop 1
	v_mov_b32_e32 v193, s0
	v_add_f32_e32 v193, s1, v193
	v_add_f32_e32 v193, s6, v193
	v_add_f32_e32 v193, s7, v193
	v_fmamk_f32 v193, v193, 0x3a800000, v212
	v_rsq_f32_e32 v213, v193
	s_nop 0
	v_mul_f32_e32 v194, v213, v194
	v_mul_f32_e32 v195, v213, v195
	v_mul_f32_e32 v196, v213, v196
	v_mul_f32_e32 v197, v213, v197
	v_mul_f32_e32 v198, v213, v198
	v_mul_f32_e32 v199, v213, v199
	v_mul_f32_e32 v200, v213, v200
	v_mul_f32_e32 v201, v213, v201
	v_mul_f32_e32 v202, v213, v202
	v_mul_f32_e32 v203, v213, v203
	v_mul_f32_e32 v204, v213, v204
	v_mul_f32_e32 v205, v213, v205
	v_mul_f32_e32 v206, v213, v206
	v_mul_f32_e32 v207, v213, v207
	v_mul_f32_e32 v208, v213, v208
	v_mul_f32_e32 v209, v213, v209
	v_fmac_f32_e32 v16, v96, v194
	v_fmac_f32_e32 v17, v97, v195
	v_fmac_f32_e32 v18, v98, v196
	v_fmac_f32_e32 v19, v99, v197
	v_fmac_f32_e32 v20, v100, v198
	v_fmac_f32_e32 v21, v101, v199
	v_fmac_f32_e32 v22, v102, v200
	v_fmac_f32_e32 v23, v103, v201
	v_fmac_f32_e32 v24, v104, v202
	v_fmac_f32_e32 v25, v105, v203
	v_fmac_f32_e32 v26, v106, v204
	v_fmac_f32_e32 v27, v107, v205
	v_fmac_f32_e32 v28, v108, v206
	v_fmac_f32_e32 v29, v109, v207
	v_fmac_f32_e32 v30, v110, v208
	v_fmac_f32_e32 v31, v111, v209
	global_store_dwordx4 v210, v[16:19], s[18:19] nt
	global_store_dwordx4 v210, v[20:23], s[18:19] offset:1024 nt
	global_store_dwordx4 v210, v[24:27], s[18:19] offset:2048 nt
	global_store_dwordx4 v210, v[28:31], s[18:19] offset:3072 nt
	v_mul_f32_e32 v192, v16, v16
	v_fmac_f32_e32 v192, v17, v17
	v_fmac_f32_e32 v192, v18, v18
	v_fmac_f32_e32 v192, v19, v19
	v_fmac_f32_e32 v192, v20, v20
	v_fmac_f32_e32 v192, v21, v21
	v_fmac_f32_e32 v192, v22, v22
	v_fmac_f32_e32 v192, v23, v23
	v_fmac_f32_e32 v192, v24, v24
	v_fmac_f32_e32 v192, v25, v25
	v_fmac_f32_e32 v192, v26, v26
	v_fmac_f32_e32 v192, v27, v27
	v_fmac_f32_e32 v192, v28, v28
	v_fmac_f32_e32 v192, v29, v29
	v_fmac_f32_e32 v192, v30, v30
	v_fmac_f32_e32 v192, v31, v31
	s_nop 1
	v_add_f32_dpp v193, v192, v192 quad_perm:[1,0,3,2] row_mask:0xf bank_mask:0xf
	s_nop 1
	v_add_f32_dpp v192, v193, v193 quad_perm:[2,3,0,1] row_mask:0xf bank_mask:0xf
	s_nop 1
	v_add_f32_dpp v193, v192, v192 row_half_mirror row_mask:0xf bank_mask:0xf
	s_nop 1
	v_add_f32_dpp v192, v193, v193 row_mirror row_mask:0xf bank_mask:0xf
	s_nop 0
	v_readlane_b32 s0, v192, 0
	v_readlane_b32 s1, v192, 16
	v_readlane_b32 s6, v192, 32
	v_readlane_b32 s7, v192, 48
	s_nop 1
	v_mov_b32_e32 v193, s0
	v_add_f32_e32 v193, s1, v193
	v_add_f32_e32 v193, s6, v193
	v_add_f32_e32 v193, s7, v193
	v_fmamk_f32 v193, v193, 0x3a800000, v212
	v_rsq_f32_e32 v213, v193
	s_nop 0
	v_mul_f32_e32 v194, v16, v213
	v_mul_f32_e32 v195, v17, v213
	v_mul_f32_e32 v196, v18, v213
	v_mul_f32_e32 v197, v19, v213
	v_mul_f32_e32 v198, v20, v213
	v_mul_f32_e32 v199, v21, v213
	v_mul_f32_e32 v200, v22, v213
	v_mul_f32_e32 v201, v23, v213
	v_mul_f32_e32 v202, v24, v213
	v_mul_f32_e32 v203, v25, v213
	v_mul_f32_e32 v204, v26, v213
	v_mul_f32_e32 v205, v27, v213
	v_mul_f32_e32 v206, v28, v213
	v_mul_f32_e32 v207, v29, v213
	v_mul_f32_e32 v208, v30, v213
	v_mul_f32_e32 v209, v31, v213
	v_mul_f32_e32 v194, v128, v194
	v_mul_f32_e32 v195, v129, v195
	v_mul_f32_e32 v196, v130, v196
	v_mul_f32_e32 v197, v131, v197
	v_mul_f32_e32 v198, v132, v198
	v_mul_f32_e32 v199, v133, v199
	v_mul_f32_e32 v200, v134, v200
	v_mul_f32_e32 v201, v135, v201
	v_mul_f32_e32 v202, v136, v202
	v_mul_f32_e32 v203, v137, v203
	v_mul_f32_e32 v204, v138, v204
	v_mul_f32_e32 v205, v139, v205
	v_mul_f32_e32 v206, v140, v206
	v_mul_f32_e32 v207, v141, v207
	v_mul_f32_e32 v208, v142, v208
	v_mul_f32_e32 v209, v143, v209
	v_fma_f32 v194, v194, v160, v144
	v_fma_f32 v195, v195, v161, v145
	v_fma_f32 v196, v196, v162, v146
	v_fma_f32 v197, v197, v163, v147
	v_fma_f32 v198, v198, v164, v148
	v_fma_f32 v199, v199, v165, v149
	v_fma_f32 v200, v200, v166, v150
	v_fma_f32 v201, v201, v167, v151
	v_fma_f32 v202, v202, v168, v152
	v_fma_f32 v203, v203, v169, v153
	v_fma_f32 v204, v204, v170, v154
	v_fma_f32 v205, v205, v171, v155
	v_fma_f32 v206, v206, v172, v156
	v_fma_f32 v207, v207, v173, v157
	v_fma_f32 v208, v208, v174, v158
	v_fma_f32 v209, v209, v175, v159
	v_cvt_pk_bf16_f32 v194, v194, v195
	v_cvt_pk_bf16_f32 v195, v196, v197
	v_cvt_pk_bf16_f32 v196, v198, v199
	v_cvt_pk_bf16_f32 v197, v200, v201
	v_cvt_pk_bf16_f32 v198, v202, v203
	v_cvt_pk_bf16_f32 v199, v204, v205
	v_cvt_pk_bf16_f32 v200, v206, v207
	v_cvt_pk_bf16_f32 v201, v208, v209
	global_store_dwordx2 v211, v[194:195], s[24:25]
	global_store_dwordx2 v211, v[196:197], s[24:25] offset:512
	global_store_dwordx2 v211, v[198:199], s[24:25] offset:1024
	global_store_dwordx2 v211, v[200:201], s[24:25] offset:1536
	s_waitcnt vmcnt(24)
	v_lshlrev_b32_e32 v176, 16, v8
	v_and_b32_e32 v177, 0xffff0000, v8
	v_lshlrev_b32_e32 v178, 16, v9
	v_and_b32_e32 v179, 0xffff0000, v9
	v_lshlrev_b32_e32 v180, 16, v10
	v_and_b32_e32 v181, 0xffff0000, v10
	v_lshlrev_b32_e32 v182, 16, v11
	v_and_b32_e32 v183, 0xffff0000, v11
	v_lshlrev_b32_e32 v184, 16, v12
	v_and_b32_e32 v185, 0xffff0000, v12
	v_lshlrev_b32_e32 v186, 16, v13
	v_and_b32_e32 v187, 0xffff0000, v13
	v_lshlrev_b32_e32 v188, 16, v14
	v_and_b32_e32 v189, 0xffff0000, v14
	v_lshlrev_b32_e32 v190, 16, v15
	v_and_b32_e32 v191, 0xffff0000, v15
	v_mul_f32_e32 v192, v176, v176
	v_fmac_f32_e32 v192, v177, v177
	v_fmac_f32_e32 v192, v178, v178
	v_fmac_f32_e32 v192, v179, v179
	v_fmac_f32_e32 v192, v180, v180
	v_fmac_f32_e32 v192, v181, v181
	v_fmac_f32_e32 v192, v182, v182
	v_fmac_f32_e32 v192, v183, v183
	v_fmac_f32_e32 v192, v184, v184
	v_fmac_f32_e32 v192, v185, v185
	v_fmac_f32_e32 v192, v186, v186
	v_fmac_f32_e32 v192, v187, v187
	v_fmac_f32_e32 v192, v188, v188
	v_fmac_f32_e32 v192, v189, v189
	v_fmac_f32_e32 v192, v190, v190
	v_fmac_f32_e32 v192, v191, v191
	v_mul_f32_e32 v194, v112, v176
	v_mul_f32_e32 v195, v113, v177
	v_mul_f32_e32 v196, v114, v178
	v_mul_f32_e32 v197, v115, v179
	v_mul_f32_e32 v198, v116, v180
	v_mul_f32_e32 v199, v117, v181
	v_mul_f32_e32 v200, v118, v182
	v_mul_f32_e32 v201, v119, v183
	v_mul_f32_e32 v202, v120, v184
	v_mul_f32_e32 v203, v121, v185
	v_mul_f32_e32 v204, v122, v186
	v_mul_f32_e32 v205, v123, v187
	v_mul_f32_e32 v206, v124, v188
	v_mul_f32_e32 v207, v125, v189
	v_mul_f32_e32 v208, v126, v190
	v_mul_f32_e32 v209, v127, v191
	s_nop 1
	v_add_f32_dpp v193, v192, v192 quad_perm:[1,0,3,2] row_mask:0xf bank_mask:0xf
	s_nop 1
	v_add_f32_dpp v192, v193, v193 quad_perm:[2,3,0,1] row_mask:0xf bank_mask:0xf
	s_nop 1
	v_add_f32_dpp v193, v192, v192 row_half_mirror row_mask:0xf bank_mask:0xf
	s_nop 1
	v_add_f32_dpp v192, v193, v193 row_mirror row_mask:0xf bank_mask:0xf
	s_nop 0
	v_readlane_b32 s0, v192, 0
	v_readlane_b32 s1, v192, 16
	v_readlane_b32 s6, v192, 32
	v_readlane_b32 s7, v192, 48
	s_nop 1
	v_mov_b32_e32 v193, s0
	v_add_f32_e32 v193, s1, v193
	v_add_f32_e32 v193, s6, v193
	v_add_f32_e32 v193, s7, v193
	v_fmamk_f32 v193, v193, 0x3a800000, v212
	v_rsq_f32_e32 v213, v193
	s_nop 0
	v_mul_f32_e32 v194, v213, v194
	v_mul_f32_e32 v195, v213, v195
	v_mul_f32_e32 v196, v213, v196
	v_mul_f32_e32 v197, v213, v197
	v_mul_f32_e32 v198, v213, v198
	v_mul_f32_e32 v199, v213, v199
	v_mul_f32_e32 v200, v213, v200
	v_mul_f32_e32 v201, v213, v201
	v_mul_f32_e32 v202, v213, v202
	v_mul_f32_e32 v203, v213, v203
	v_mul_f32_e32 v204, v213, v204
	v_mul_f32_e32 v205, v213, v205
	v_mul_f32_e32 v206, v213, v206
	v_mul_f32_e32 v207, v213, v207
	v_mul_f32_e32 v208, v213, v208
	v_mul_f32_e32 v209, v213, v209
	v_fmac_f32_e32 v32, v96, v194
	v_fmac_f32_e32 v33, v97, v195
	v_fmac_f32_e32 v34, v98, v196
	v_fmac_f32_e32 v35, v99, v197
	v_fmac_f32_e32 v36, v100, v198
	v_fmac_f32_e32 v37, v101, v199
	v_fmac_f32_e32 v38, v102, v200
	v_fmac_f32_e32 v39, v103, v201
	v_fmac_f32_e32 v40, v104, v202
	v_fmac_f32_e32 v41, v105, v203
	v_fmac_f32_e32 v42, v106, v204
	v_fmac_f32_e32 v43, v107, v205
	v_fmac_f32_e32 v44, v108, v206
	v_fmac_f32_e32 v45, v109, v207
	v_fmac_f32_e32 v46, v110, v208
	v_fmac_f32_e32 v47, v111, v209
	global_store_dwordx4 v210, v[32:35], s[20:21] nt
	global_store_dwordx4 v210, v[36:39], s[20:21] offset:1024 nt
	global_store_dwordx4 v210, v[40:43], s[20:21] offset:2048 nt
	global_store_dwordx4 v210, v[44:47], s[20:21] offset:3072 nt
	v_mul_f32_e32 v192, v32, v32
	v_fmac_f32_e32 v192, v33, v33
	v_fmac_f32_e32 v192, v34, v34
	v_fmac_f32_e32 v192, v35, v35
	v_fmac_f32_e32 v192, v36, v36
	v_fmac_f32_e32 v192, v37, v37
	v_fmac_f32_e32 v192, v38, v38
	v_fmac_f32_e32 v192, v39, v39
	v_fmac_f32_e32 v192, v40, v40
	v_fmac_f32_e32 v192, v41, v41
	v_fmac_f32_e32 v192, v42, v42
	v_fmac_f32_e32 v192, v43, v43
	v_fmac_f32_e32 v192, v44, v44
	v_fmac_f32_e32 v192, v45, v45
	v_fmac_f32_e32 v192, v46, v46
	v_fmac_f32_e32 v192, v47, v47
	s_nop 1
	v_add_f32_dpp v193, v192, v192 quad_perm:[1,0,3,2] row_mask:0xf bank_mask:0xf
	s_nop 1
	v_add_f32_dpp v192, v193, v193 quad_perm:[2,3,0,1] row_mask:0xf bank_mask:0xf
	s_nop 1
	v_add_f32_dpp v193, v192, v192 row_half_mirror row_mask:0xf bank_mask:0xf
	s_nop 1
	v_add_f32_dpp v192, v193, v193 row_mirror row_mask:0xf bank_mask:0xf
	s_nop 0
	v_readlane_b32 s0, v192, 0
	v_readlane_b32 s1, v192, 16
	v_readlane_b32 s6, v192, 32
	v_readlane_b32 s7, v192, 48
	s_nop 1
	v_mov_b32_e32 v193, s0
	v_add_f32_e32 v193, s1, v193
	v_add_f32_e32 v193, s6, v193
	v_add_f32_e32 v193, s7, v193
	v_fmamk_f32 v193, v193, 0x3a800000, v212
	v_rsq_f32_e32 v213, v193
	s_nop 0
	v_mul_f32_e32 v194, v32, v213
	v_mul_f32_e32 v195, v33, v213
	v_mul_f32_e32 v196, v34, v213
	v_mul_f32_e32 v197, v35, v213
	v_mul_f32_e32 v198, v36, v213
	v_mul_f32_e32 v199, v37, v213
	v_mul_f32_e32 v200, v38, v213
	v_mul_f32_e32 v201, v39, v213
	v_mul_f32_e32 v202, v40, v213
	v_mul_f32_e32 v203, v41, v213
	v_mul_f32_e32 v204, v42, v213
	v_mul_f32_e32 v205, v43, v213
	v_mul_f32_e32 v206, v44, v213
	v_mul_f32_e32 v207, v45, v213
	v_mul_f32_e32 v208, v46, v213
	v_mul_f32_e32 v209, v47, v213
	v_mul_f32_e32 v194, v128, v194
	v_mul_f32_e32 v195, v129, v195
	v_mul_f32_e32 v196, v130, v196
	v_mul_f32_e32 v197, v131, v197
	v_mul_f32_e32 v198, v132, v198
	v_mul_f32_e32 v199, v133, v199
	v_mul_f32_e32 v200, v134, v200
	v_mul_f32_e32 v201, v135, v201
	v_mul_f32_e32 v202, v136, v202
	v_mul_f32_e32 v203, v137, v203
	v_mul_f32_e32 v204, v138, v204
	v_mul_f32_e32 v205, v139, v205
	v_mul_f32_e32 v206, v140, v206
	v_mul_f32_e32 v207, v141, v207
	v_mul_f32_e32 v208, v142, v208
	v_mul_f32_e32 v209, v143, v209
	v_fma_f32 v194, v194, v160, v144
	v_fma_f32 v195, v195, v161, v145
	v_fma_f32 v196, v196, v162, v146
	v_fma_f32 v197, v197, v163, v147
	v_fma_f32 v198, v198, v164, v148
	v_fma_f32 v199, v199, v165, v149
	v_fma_f32 v200, v200, v166, v150
	v_fma_f32 v201, v201, v167, v151
	v_fma_f32 v202, v202, v168, v152
	v_fma_f32 v203, v203, v169, v153
	v_fma_f32 v204, v204, v170, v154
	v_fma_f32 v205, v205, v171, v155
	v_fma_f32 v206, v206, v172, v156
	v_fma_f32 v207, v207, v173, v157
	v_fma_f32 v208, v208, v174, v158
	v_fma_f32 v209, v209, v175, v159
	v_cvt_pk_bf16_f32 v194, v194, v195
	v_cvt_pk_bf16_f32 v195, v196, v197
	v_cvt_pk_bf16_f32 v196, v198, v199
	v_cvt_pk_bf16_f32 v197, v200, v201
	v_cvt_pk_bf16_f32 v198, v202, v203
	v_cvt_pk_bf16_f32 v199, v204, v205
	v_cvt_pk_bf16_f32 v200, v206, v207
	v_cvt_pk_bf16_f32 v201, v208, v209
	global_store_dwordx2 v211, v[194:195], s[36:37]
	global_store_dwordx2 v211, v[196:197], s[36:37] offset:512
	global_store_dwordx2 v211, v[198:199], s[36:37] offset:1024
	global_store_dwordx2 v211, v[200:201], s[36:37] offset:1536
	s_add_u32 s18, s18, 0x400000
	s_addc_u32 s19, s19, 0
	s_add_u32 s20, s20, 0x400000
	s_addc_u32 s21, s21, 0
	s_add_u32 s24, s24, 0x200000
	s_addc_u32 s25, s25, 0
	s_add_u32 s36, s36, 0x200000
	s_addc_u32 s37, s37, 0
	s_cmp_eq_u32 s4, 3
	s_cbranch_scc1 .Lpost0_last
	s_add_u32 s10, s10, 0x800000
	s_addc_u32 s11, s11, 0
	s_add_u32 s12, s12, 0x800000
	s_addc_u32 s13, s13, 0
	s_add_u32 s14, s14, 0x400000
	s_addc_u32 s15, s15, 0
	s_add_u32 s16, s16, 0x400000
	s_addc_u32 s17, s17, 0
	global_load_dwordx2 v[0:1], v211, s[10:11] nt
	global_load_dwordx2 v[2:3], v211, s[10:11] offset:512 nt
	global_load_dwordx2 v[4:5], v211, s[10:11] offset:1024 nt
	global_load_dwordx2 v[6:7], v211, s[10:11] offset:1536 nt
	global_load_dwordx4 v[16:19], v210, s[14:15] nt
	global_load_dwordx4 v[20:23], v210, s[14:15] offset:1024 nt
	global_load_dwordx4 v[24:27], v210, s[14:15] offset:2048 nt
	global_load_dwordx4 v[28:31], v210, s[14:15] offset:3072 nt
	global_load_dwordx2 v[8:9], v211, s[12:13] nt
	global_load_dwordx2 v[10:11], v211, s[12:13] offset:512 nt
	global_load_dwordx2 v[12:13], v211, s[12:13] offset:1024 nt
	global_load_dwordx2 v[14:15], v211, s[12:13] offset:1536 nt
	global_load_dwordx4 v[32:35], v210, s[16:17] nt
	global_load_dwordx4 v[36:39], v210, s[16:17] offset:1024 nt
	global_load_dwordx4 v[40:43], v210, s[16:17] offset:2048 nt
	global_load_dwordx4 v[44:47], v210, s[16:17] offset:3072 nt
	s_waitcnt vmcnt(40)
	v_lshlrev_b32_e32 v176, 16, v48
	v_and_b32_e32 v177, 0xffff0000, v48
	v_lshlrev_b32_e32 v178, 16, v49
	v_and_b32_e32 v179, 0xffff0000, v49
	v_lshlrev_b32_e32 v180, 16, v50
	v_and_b32_e32 v181, 0xffff0000, v50
	v_lshlrev_b32_e32 v182, 16, v51
	v_and_b32_e32 v183, 0xffff0000, v51
	v_lshlrev_b32_e32 v184, 16, v52
	v_and_b32_e32 v185, 0xffff0000, v52
	v_lshlrev_b32_e32 v186, 16, v53
	v_and_b32_e32 v187, 0xffff0000, v53
	v_lshlrev_b32_e32 v188, 16, v54
	v_and_b32_e32 v189, 0xffff0000, v54
	v_lshlrev_b32_e32 v190, 16, v55
	v_and_b32_e32 v191, 0xffff0000, v55
	v_mul_f32_e32 v192, v176, v176
	v_fmac_f32_e32 v192, v177, v177
	v_fmac_f32_e32 v192, v178, v178
	v_fmac_f32_e32 v192, v179, v179
	v_fmac_f32_e32 v192, v180, v180
	v_fmac_f32_e32 v192, v181, v181
	v_fmac_f32_e32 v192, v182, v182
	v_fmac_f32_e32 v192, v183, v183
	v_fmac_f32_e32 v192, v184, v184
	v_fmac_f32_e32 v192, v185, v185
	v_fmac_f32_e32 v192, v186, v186
	v_fmac_f32_e32 v192, v187, v187
	v_fmac_f32_e32 v192, v188, v188
	v_fmac_f32_e32 v192, v189, v189
	v_fmac_f32_e32 v192, v190, v190
	v_fmac_f32_e32 v192, v191, v191
	v_mul_f32_e32 v194, v112, v176
	v_mul_f32_e32 v195, v113, v177
	v_mul_f32_e32 v196, v114, v178
	v_mul_f32_e32 v197, v115, v179
	v_mul_f32_e32 v198, v116, v180
	v_mul_f32_e32 v199, v117, v181
	v_mul_f32_e32 v200, v118, v182
	v_mul_f32_e32 v201, v119, v183
	v_mul_f32_e32 v202, v120, v184
	v_mul_f32_e32 v203, v121, v185
	v_mul_f32_e32 v204, v122, v186
	v_mul_f32_e32 v205, v123, v187
	v_mul_f32_e32 v206, v124, v188
	v_mul_f32_e32 v207, v125, v189
	v_mul_f32_e32 v208, v126, v190
	v_mul_f32_e32 v209, v127, v191
	s_nop 1
	v_add_f32_dpp v193, v192, v192 quad_perm:[1,0,3,2] row_mask:0xf bank_mask:0xf
	s_nop 1
	v_add_f32_dpp v192, v193, v193 quad_perm:[2,3,0,1] row_mask:0xf bank_mask:0xf
	s_nop 1
	v_add_f32_dpp v193, v192, v192 row_half_mirror row_mask:0xf bank_mask:0xf
	s_nop 1
	v_add_f32_dpp v192, v193, v193 row_mirror row_mask:0xf bank_mask:0xf
	s_nop 0
	v_readlane_b32 s0, v192, 0
	v_readlane_b32 s1, v192, 16
	v_readlane_b32 s6, v192, 32
	v_readlane_b32 s7, v192, 48
	s_nop 1
	v_mov_b32_e32 v193, s0
	v_add_f32_e32 v193, s1, v193
	v_add_f32_e32 v193, s6, v193
	v_add_f32_e32 v193, s7, v193
	v_fmamk_f32 v193, v193, 0x3a800000, v212
	v_rsq_f32_e32 v213, v193
	s_nop 0
	v_mul_f32_e32 v194, v213, v194
	v_mul_f32_e32 v195, v213, v195
	v_mul_f32_e32 v196, v213, v196
	v_mul_f32_e32 v197, v213, v197
	v_mul_f32_e32 v198, v213, v198
	v_mul_f32_e32 v199, v213, v199
	v_mul_f32_e32 v200, v213, v200
	v_mul_f32_e32 v201, v213, v201
	v_mul_f32_e32 v202, v213, v202
	v_mul_f32_e32 v203, v213, v203
	v_mul_f32_e32 v204, v213, v204
	v_mul_f32_e32 v205, v213, v205
	v_mul_f32_e32 v206, v213, v206
	v_mul_f32_e32 v207, v213, v207
	v_mul_f32_e32 v208, v213, v208
	v_mul_f32_e32 v209, v213, v209
	v_fmac_f32_e32 v64, v96, v194
	v_fmac_f32_e32 v65, v97, v195
	v_fmac_f32_e32 v66, v98, v196
	v_fmac_f32_e32 v67, v99, v197
	v_fmac_f32_e32 v68, v100, v198
	v_fmac_f32_e32 v69, v101, v199
	v_fmac_f32_e32 v70, v102, v200
	v_fmac_f32_e32 v71, v103, v201
	v_fmac_f32_e32 v72, v104, v202
	v_fmac_f32_e32 v73, v105, v203
	v_fmac_f32_e32 v74, v106, v204
	v_fmac_f32_e32 v75, v107, v205
	v_fmac_f32_e32 v76, v108, v206
	v_fmac_f32_e32 v77, v109, v207
	v_fmac_f32_e32 v78, v110, v208
	v_fmac_f32_e32 v79, v111, v209
	global_store_dwordx4 v210, v[64:67], s[18:19] nt
	global_store_dwordx4 v210, v[68:71], s[18:19] offset:1024 nt
	global_store_dwordx4 v210, v[72:75], s[18:19] offset:2048 nt
	global_store_dwordx4 v210, v[76:79], s[18:19] offset:3072 nt
	v_mul_f32_e32 v192, v64, v64
	v_fmac_f32_e32 v192, v65, v65
	v_fmac_f32_e32 v192, v66, v66
	v_fmac_f32_e32 v192, v67, v67
	v_fmac_f32_e32 v192, v68, v68
	v_fmac_f32_e32 v192, v69, v69
	v_fmac_f32_e32 v192, v70, v70
	v_fmac_f32_e32 v192, v71, v71
	v_fmac_f32_e32 v192, v72, v72
	v_fmac_f32_e32 v192, v73, v73
	v_fmac_f32_e32 v192, v74, v74
	v_fmac_f32_e32 v192, v75, v75
	v_fmac_f32_e32 v192, v76, v76
	v_fmac_f32_e32 v192, v77, v77
	v_fmac_f32_e32 v192, v78, v78
	v_fmac_f32_e32 v192, v79, v79
	s_nop 1
	v_add_f32_dpp v193, v192, v192 quad_perm:[1,0,3,2] row_mask:0xf bank_mask:0xf
	s_nop 1
	v_add_f32_dpp v192, v193, v193 quad_perm:[2,3,0,1] row_mask:0xf bank_mask:0xf
	s_nop 1
	v_add_f32_dpp v193, v192, v192 row_half_mirror row_mask:0xf bank_mask:0xf
	s_nop 1
	v_add_f32_dpp v192, v193, v193 row_mirror row_mask:0xf bank_mask:0xf
	s_nop 0
	v_readlane_b32 s0, v192, 0
	v_readlane_b32 s1, v192, 16
	v_readlane_b32 s6, v192, 32
	v_readlane_b32 s7, v192, 48
	s_nop 1
	v_mov_b32_e32 v193, s0
	v_add_f32_e32 v193, s1, v193
	v_add_f32_e32 v193, s6, v193
	v_add_f32_e32 v193, s7, v193
	v_fmamk_f32 v193, v193, 0x3a800000, v212
	v_rsq_f32_e32 v213, v193
	s_nop 0
	v_mul_f32_e32 v194, v64, v213
	v_mul_f32_e32 v195, v65, v213
	v_mul_f32_e32 v196, v66, v213
	v_mul_f32_e32 v197, v67, v213
	v_mul_f32_e32 v198, v68, v213
	v_mul_f32_e32 v199, v69, v213
	v_mul_f32_e32 v200, v70, v213
	v_mul_f32_e32 v201, v71, v213
	v_mul_f32_e32 v202, v72, v213
	v_mul_f32_e32 v203, v73, v213
	v_mul_f32_e32 v204, v74, v213
	v_mul_f32_e32 v205, v75, v213
	v_mul_f32_e32 v206, v76, v213
	v_mul_f32_e32 v207, v77, v213
	v_mul_f32_e32 v208, v78, v213
	v_mul_f32_e32 v209, v79, v213
	v_mul_f32_e32 v194, v128, v194
	v_mul_f32_e32 v195, v129, v195
	v_mul_f32_e32 v196, v130, v196
	v_mul_f32_e32 v197, v131, v197
	v_mul_f32_e32 v198, v132, v198
	v_mul_f32_e32 v199, v133, v199
	v_mul_f32_e32 v200, v134, v200
	v_mul_f32_e32 v201, v135, v201
	v_mul_f32_e32 v202, v136, v202
	v_mul_f32_e32 v203, v137, v203
	v_mul_f32_e32 v204, v138, v204
	v_mul_f32_e32 v205, v139, v205
	v_mul_f32_e32 v206, v140, v206
	v_mul_f32_e32 v207, v141, v207
	v_mul_f32_e32 v208, v142, v208
	v_mul_f32_e32 v209, v143, v209
	v_fma_f32 v194, v194, v160, v144
	v_fma_f32 v195, v195, v161, v145
	v_fma_f32 v196, v196, v162, v146
	v_fma_f32 v197, v197, v163, v147
	v_fma_f32 v198, v198, v164, v148
	v_fma_f32 v199, v199, v165, v149
	v_fma_f32 v200, v200, v166, v150
	v_fma_f32 v201, v201, v167, v151
	v_fma_f32 v202, v202, v168, v152
	v_fma_f32 v203, v203, v169, v153
	v_fma_f32 v204, v204, v170, v154
	v_fma_f32 v205, v205, v171, v155
	v_fma_f32 v206, v206, v172, v156
	v_fma_f32 v207, v207, v173, v157
	v_fma_f32 v208, v208, v174, v158
	v_fma_f32 v209, v209, v175, v159
	v_cvt_pk_bf16_f32 v194, v194, v195
	v_cvt_pk_bf16_f32 v195, v196, v197
	v_cvt_pk_bf16_f32 v196, v198, v199
	v_cvt_pk_bf16_f32 v197, v200, v201
	v_cvt_pk_bf16_f32 v198, v202, v203
	v_cvt_pk_bf16_f32 v199, v204, v205
	v_cvt_pk_bf16_f32 v200, v206, v207
	v_cvt_pk_bf16_f32 v201, v208, v209
	global_store_dwordx2 v211, v[194:195], s[24:25]
	global_store_dwordx2 v211, v[196:197], s[24:25] offset:512
	global_store_dwordx2 v211, v[198:199], s[24:25] offset:1024
	global_store_dwordx2 v211, v[200:201], s[24:25] offset:1536
	s_waitcnt vmcnt(24)
	v_lshlrev_b32_e32 v176, 16, v56
	v_and_b32_e32 v177, 0xffff0000, v56
	v_lshlrev_b32_e32 v178, 16, v57
	v_and_b32_e32 v179, 0xffff0000, v57
	v_lshlrev_b32_e32 v180, 16, v58
	v_and_b32_e32 v181, 0xffff0000, v58
	v_lshlrev_b32_e32 v182, 16, v59
	v_and_b32_e32 v183, 0xffff0000, v59
	v_lshlrev_b32_e32 v184, 16, v60
	v_and_b32_e32 v185, 0xffff0000, v60
	v_lshlrev_b32_e32 v186, 16, v61
	v_and_b32_e32 v187, 0xffff0000, v61
	v_lshlrev_b32_e32 v188, 16, v62
	v_and_b32_e32 v189, 0xffff0000, v62
	v_lshlrev_b32_e32 v190, 16, v63
	v_and_b32_e32 v191, 0xffff0000, v63
	v_mul_f32_e32 v192, v176, v176
	v_fmac_f32_e32 v192, v177, v177
	v_fmac_f32_e32 v192, v178, v178
	v_fmac_f32_e32 v192, v179, v179
	v_fmac_f32_e32 v192, v180, v180
	v_fmac_f32_e32 v192, v181, v181
	v_fmac_f32_e32 v192, v182, v182
	v_fmac_f32_e32 v192, v183, v183
	v_fmac_f32_e32 v192, v184, v184
	v_fmac_f32_e32 v192, v185, v185
	v_fmac_f32_e32 v192, v186, v186
	v_fmac_f32_e32 v192, v187, v187
	v_fmac_f32_e32 v192, v188, v188
	v_fmac_f32_e32 v192, v189, v189
	v_fmac_f32_e32 v192, v190, v190
	v_fmac_f32_e32 v192, v191, v191
	v_mul_f32_e32 v194, v112, v176
	v_mul_f32_e32 v195, v113, v177
	v_mul_f32_e32 v196, v114, v178
	v_mul_f32_e32 v197, v115, v179
	v_mul_f32_e32 v198, v116, v180
	v_mul_f32_e32 v199, v117, v181
	v_mul_f32_e32 v200, v118, v182
	v_mul_f32_e32 v201, v119, v183
	v_mul_f32_e32 v202, v120, v184
	v_mul_f32_e32 v203, v121, v185
	v_mul_f32_e32 v204, v122, v186
	v_mul_f32_e32 v205, v123, v187
	v_mul_f32_e32 v206, v124, v188
	v_mul_f32_e32 v207, v125, v189
	v_mul_f32_e32 v208, v126, v190
	v_mul_f32_e32 v209, v127, v191
	s_nop 1
	v_add_f32_dpp v193, v192, v192 quad_perm:[1,0,3,2] row_mask:0xf bank_mask:0xf
	s_nop 1
	v_add_f32_dpp v192, v193, v193 quad_perm:[2,3,0,1] row_mask:0xf bank_mask:0xf
	s_nop 1
	v_add_f32_dpp v193, v192, v192 row_half_mirror row_mask:0xf bank_mask:0xf
	s_nop 1
	v_add_f32_dpp v192, v193, v193 row_mirror row_mask:0xf bank_mask:0xf
	s_nop 0
	v_readlane_b32 s0, v192, 0
	v_readlane_b32 s1, v192, 16
	v_readlane_b32 s6, v192, 32
	v_readlane_b32 s7, v192, 48
	s_nop 1
	v_mov_b32_e32 v193, s0
	v_add_f32_e32 v193, s1, v193
	v_add_f32_e32 v193, s6, v193
	v_add_f32_e32 v193, s7, v193
	v_fmamk_f32 v193, v193, 0x3a800000, v212
	v_rsq_f32_e32 v213, v193
	s_nop 0
	v_mul_f32_e32 v194, v213, v194
	v_mul_f32_e32 v195, v213, v195
	v_mul_f32_e32 v196, v213, v196
	v_mul_f32_e32 v197, v213, v197
	v_mul_f32_e32 v198, v213, v198
	v_mul_f32_e32 v199, v213, v199
	v_mul_f32_e32 v200, v213, v200
	v_mul_f32_e32 v201, v213, v201
	v_mul_f32_e32 v202, v213, v202
	v_mul_f32_e32 v203, v213, v203
	v_mul_f32_e32 v204, v213, v204
	v_mul_f32_e32 v205, v213, v205
	v_mul_f32_e32 v206, v213, v206
	v_mul_f32_e32 v207, v213, v207
	v_mul_f32_e32 v208, v213, v208
	v_mul_f32_e32 v209, v213, v209
	v_fmac_f32_e32 v80, v96, v194
	v_fmac_f32_e32 v81, v97, v195
	v_fmac_f32_e32 v82, v98, v196
	v_fmac_f32_e32 v83, v99, v197
	v_fmac_f32_e32 v84, v100, v198
	v_fmac_f32_e32 v85, v101, v199
	v_fmac_f32_e32 v86, v102, v200
	v_fmac_f32_e32 v87, v103, v201
	v_fmac_f32_e32 v88, v104, v202
	v_fmac_f32_e32 v89, v105, v203
	v_fmac_f32_e32 v90, v106, v204
	v_fmac_f32_e32 v91, v107, v205
	v_fmac_f32_e32 v92, v108, v206
	v_fmac_f32_e32 v93, v109, v207
	v_fmac_f32_e32 v94, v110, v208
	v_fmac_f32_e32 v95, v111, v209
	global_store_dwordx4 v210, v[80:83], s[20:21] nt
	global_store_dwordx4 v210, v[84:87], s[20:21] offset:1024 nt
	global_store_dwordx4 v210, v[88:91], s[20:21] offset:2048 nt
	global_store_dwordx4 v210, v[92:95], s[20:21] offset:3072 nt
	v_mul_f32_e32 v192, v80, v80
	v_fmac_f32_e32 v192, v81, v81
	v_fmac_f32_e32 v192, v82, v82
	v_fmac_f32_e32 v192, v83, v83
	v_fmac_f32_e32 v192, v84, v84
	v_fmac_f32_e32 v192, v85, v85
	v_fmac_f32_e32 v192, v86, v86
	v_fmac_f32_e32 v192, v87, v87
	v_fmac_f32_e32 v192, v88, v88
	v_fmac_f32_e32 v192, v89, v89
	v_fmac_f32_e32 v192, v90, v90
	v_fmac_f32_e32 v192, v91, v91
	v_fmac_f32_e32 v192, v92, v92
	v_fmac_f32_e32 v192, v93, v93
	v_fmac_f32_e32 v192, v94, v94
	v_fmac_f32_e32 v192, v95, v95
	s_nop 1
	v_add_f32_dpp v193, v192, v192 quad_perm:[1,0,3,2] row_mask:0xf bank_mask:0xf
	s_nop 1
	v_add_f32_dpp v192, v193, v193 quad_perm:[2,3,0,1] row_mask:0xf bank_mask:0xf
	s_nop 1
	v_add_f32_dpp v193, v192, v192 row_half_mirror row_mask:0xf bank_mask:0xf
	s_nop 1
	v_add_f32_dpp v192, v193, v193 row_mirror row_mask:0xf bank_mask:0xf
	s_nop 0
	v_readlane_b32 s0, v192, 0
	v_readlane_b32 s1, v192, 16
	v_readlane_b32 s6, v192, 32
	v_readlane_b32 s7, v192, 48
	s_nop 1
	v_mov_b32_e32 v193, s0
	v_add_f32_e32 v193, s1, v193
	v_add_f32_e32 v193, s6, v193
	v_add_f32_e32 v193, s7, v193
	v_fmamk_f32 v193, v193, 0x3a800000, v212
	v_rsq_f32_e32 v213, v193
	s_nop 0
	v_mul_f32_e32 v194, v80, v213
	v_mul_f32_e32 v195, v81, v213
	v_mul_f32_e32 v196, v82, v213
	v_mul_f32_e32 v197, v83, v213
	v_mul_f32_e32 v198, v84, v213
	v_mul_f32_e32 v199, v85, v213
	v_mul_f32_e32 v200, v86, v213
	v_mul_f32_e32 v201, v87, v213
	v_mul_f32_e32 v202, v88, v213
	v_mul_f32_e32 v203, v89, v213
	v_mul_f32_e32 v204, v90, v213
	v_mul_f32_e32 v205, v91, v213
	v_mul_f32_e32 v206, v92, v213
	v_mul_f32_e32 v207, v93, v213
	v_mul_f32_e32 v208, v94, v213
	v_mul_f32_e32 v209, v95, v213
	v_mul_f32_e32 v194, v128, v194
	v_mul_f32_e32 v195, v129, v195
	v_mul_f32_e32 v196, v130, v196
	v_mul_f32_e32 v197, v131, v197
	v_mul_f32_e32 v198, v132, v198
	v_mul_f32_e32 v199, v133, v199
	v_mul_f32_e32 v200, v134, v200
	v_mul_f32_e32 v201, v135, v201
	v_mul_f32_e32 v202, v136, v202
	v_mul_f32_e32 v203, v137, v203
	v_mul_f32_e32 v204, v138, v204
	v_mul_f32_e32 v205, v139, v205
	v_mul_f32_e32 v206, v140, v206
	v_mul_f32_e32 v207, v141, v207
	v_mul_f32_e32 v208, v142, v208
	v_mul_f32_e32 v209, v143, v209
	v_fma_f32 v194, v194, v160, v144
	v_fma_f32 v195, v195, v161, v145
	v_fma_f32 v196, v196, v162, v146
	v_fma_f32 v197, v197, v163, v147
	v_fma_f32 v198, v198, v164, v148
	v_fma_f32 v199, v199, v165, v149
	v_fma_f32 v200, v200, v166, v150
	v_fma_f32 v201, v201, v167, v151
	v_fma_f32 v202, v202, v168, v152
	v_fma_f32 v203, v203, v169, v153
	v_fma_f32 v204, v204, v170, v154
	v_fma_f32 v205, v205, v171, v155
	v_fma_f32 v206, v206, v172, v156
	v_fma_f32 v207, v207, v173, v157
	v_fma_f32 v208, v208, v174, v158
	v_fma_f32 v209, v209, v175, v159
	v_cvt_pk_bf16_f32 v194, v194, v195
	v_cvt_pk_bf16_f32 v195, v196, v197
	v_cvt_pk_bf16_f32 v196, v198, v199
	v_cvt_pk_bf16_f32 v197, v200, v201
	v_cvt_pk_bf16_f32 v198, v202, v203
	v_cvt_pk_bf16_f32 v199, v204, v205
	v_cvt_pk_bf16_f32 v200, v206, v207
	v_cvt_pk_bf16_f32 v201, v208, v209
	global_store_dwordx2 v211, v[194:195], s[36:37]
	global_store_dwordx2 v211, v[196:197], s[36:37] offset:512
	global_store_dwordx2 v211, v[198:199], s[36:37] offset:1024
	global_store_dwordx2 v211, v[200:201], s[36:37] offset:1536
	s_add_u32 s18, s18, 0x400000
	s_addc_u32 s19, s19, 0
	s_add_u32 s20, s20, 0x400000
	s_addc_u32 s21, s21, 0
	s_add_u32 s24, s24, 0x200000
	s_addc_u32 s25, s25, 0
	s_add_u32 s36, s36, 0x200000
	s_addc_u32 s37, s37, 0
	s_add_u32 s4, s4, 1
	s_branch .Lpost0_loop
.Lpost0_last:
	s_waitcnt vmcnt(24)
	v_lshlrev_b32_e32 v176, 16, v48
	v_and_b32_e32 v177, 0xffff0000, v48
	v_lshlrev_b32_e32 v178, 16, v49
	v_and_b32_e32 v179, 0xffff0000, v49
	v_lshlrev_b32_e32 v180, 16, v50
	v_and_b32_e32 v181, 0xffff0000, v50
	v_lshlrev_b32_e32 v182, 16, v51
	v_and_b32_e32 v183, 0xffff0000, v51
	v_lshlrev_b32_e32 v184, 16, v52
	v_and_b32_e32 v185, 0xffff0000, v52
	v_lshlrev_b32_e32 v186, 16, v53
	v_and_b32_e32 v187, 0xffff0000, v53
	v_lshlrev_b32_e32 v188, 16, v54
	v_and_b32_e32 v189, 0xffff0000, v54
	v_lshlrev_b32_e32 v190, 16, v55
	v_and_b32_e32 v191, 0xffff0000, v55
	v_mul_f32_e32 v192, v176, v176
	v_fmac_f32_e32 v192, v177, v177
	v_fmac_f32_e32 v192, v178, v178
	v_fmac_f32_e32 v192, v179, v179
	v_fmac_f32_e32 v192, v180, v180
	v_fmac_f32_e32 v192, v181, v181
	v_fmac_f32_e32 v192, v182, v182
	v_fmac_f32_e32 v192, v183, v183
	v_fmac_f32_e32 v192, v184, v184
	v_fmac_f32_e32 v192, v185, v185
	v_fmac_f32_e32 v192, v186, v186
	v_fmac_f32_e32 v192, v187, v187
	v_fmac_f32_e32 v192, v188, v188
	v_fmac_f32_e32 v192, v189, v189
	v_fmac_f32_e32 v192, v190, v190
	v_fmac_f32_e32 v192, v191, v191
	v_mul_f32_e32 v194, v112, v176
	v_mul_f32_e32 v195, v113, v177
	v_mul_f32_e32 v196, v114, v178
	v_mul_f32_e32 v197, v115, v179
	v_mul_f32_e32 v198, v116, v180
	v_mul_f32_e32 v199, v117, v181
	v_mul_f32_e32 v200, v118, v182
	v_mul_f32_e32 v201, v119, v183
	v_mul_f32_e32 v202, v120, v184
	v_mul_f32_e32 v203, v121, v185
	v_mul_f32_e32 v204, v122, v186
	v_mul_f32_e32 v205, v123, v187
	v_mul_f32_e32 v206, v124, v188
	v_mul_f32_e32 v207, v125, v189
	v_mul_f32_e32 v208, v126, v190
	v_mul_f32_e32 v209, v127, v191
	s_nop 1
	v_add_f32_dpp v193, v192, v192 quad_perm:[1,0,3,2] row_mask:0xf bank_mask:0xf
	s_nop 1
	v_add_f32_dpp v192, v193, v193 quad_perm:[2,3,0,1] row_mask:0xf bank_mask:0xf
	s_nop 1
	v_add_f32_dpp v193, v192, v192 row_half_mirror row_mask:0xf bank_mask:0xf
	s_nop 1
	v_add_f32_dpp v192, v193, v193 row_mirror row_mask:0xf bank_mask:0xf
	s_nop 0
	v_readlane_b32 s0, v192, 0
	v_readlane_b32 s1, v192, 16
	v_readlane_b32 s6, v192, 32
	v_readlane_b32 s7, v192, 48
	s_nop 1
	v_mov_b32_e32 v193, s0
	v_add_f32_e32 v193, s1, v193
	v_add_f32_e32 v193, s6, v193
	v_add_f32_e32 v193, s7, v193
	v_fmamk_f32 v193, v193, 0x3a800000, v212
	v_rsq_f32_e32 v213, v193
	s_nop 0
	v_mul_f32_e32 v194, v213, v194
	v_mul_f32_e32 v195, v213, v195
	v_mul_f32_e32 v196, v213, v196
	v_mul_f32_e32 v197, v213, v197
	v_mul_f32_e32 v198, v213, v198
	v_mul_f32_e32 v199, v213, v199
	v_mul_f32_e32 v200, v213, v200
	v_mul_f32_e32 v201, v213, v201
	v_mul_f32_e32 v202, v213, v202
	v_mul_f32_e32 v203, v213, v203
	v_mul_f32_e32 v204, v213, v204
	v_mul_f32_e32 v205, v213, v205
	v_mul_f32_e32 v206, v213, v206
	v_mul_f32_e32 v207, v213, v207
	v_mul_f32_e32 v208, v213, v208
	v_mul_f32_e32 v209, v213, v209
	v_fmac_f32_e32 v64, v96, v194
	v_fmac_f32_e32 v65, v97, v195
	v_fmac_f32_e32 v66, v98, v196
	v_fmac_f32_e32 v67, v99, v197
	v_fmac_f32_e32 v68, v100, v198
	v_fmac_f32_e32 v69, v101, v199
	v_fmac_f32_e32 v70, v102, v200
	v_fmac_f32_e32 v71, v103, v201
	v_fmac_f32_e32 v72, v104, v202
	v_fmac_f32_e32 v73, v105, v203
	v_fmac_f32_e32 v74, v106, v204
	v_fmac_f32_e32 v75, v107, v205
	v_fmac_f32_e32 v76, v108, v206
	v_fmac_f32_e32 v77, v109, v207
	v_fmac_f32_e32 v78, v110, v208
	v_fmac_f32_e32 v79, v111, v209
	global_store_dwordx4 v210, v[64:67], s[18:19] nt
	global_store_dwordx4 v210, v[68:71], s[18:19] offset:1024 nt
	global_store_dwordx4 v210, v[72:75], s[18:19] offset:2048 nt
	global_store_dwordx4 v210, v[76:79], s[18:19] offset:3072 nt
	v_mul_f32_e32 v192, v64, v64
	v_fmac_f32_e32 v192, v65, v65
	v_fmac_f32_e32 v192, v66, v66
	v_fmac_f32_e32 v192, v67, v67
	v_fmac_f32_e32 v192, v68, v68
	v_fmac_f32_e32 v192, v69, v69
	v_fmac_f32_e32 v192, v70, v70
	v_fmac_f32_e32 v192, v71, v71
	v_fmac_f32_e32 v192, v72, v72
	v_fmac_f32_e32 v192, v73, v73
	v_fmac_f32_e32 v192, v74, v74
	v_fmac_f32_e32 v192, v75, v75
	v_fmac_f32_e32 v192, v76, v76
	v_fmac_f32_e32 v192, v77, v77
	v_fmac_f32_e32 v192, v78, v78
	v_fmac_f32_e32 v192, v79, v79
	s_nop 1
	v_add_f32_dpp v193, v192, v192 quad_perm:[1,0,3,2] row_mask:0xf bank_mask:0xf
	s_nop 1
	v_add_f32_dpp v192, v193, v193 quad_perm:[2,3,0,1] row_mask:0xf bank_mask:0xf
	s_nop 1
	v_add_f32_dpp v193, v192, v192 row_half_mirror row_mask:0xf bank_mask:0xf
	s_nop 1
	v_add_f32_dpp v192, v193, v193 row_mirror row_mask:0xf bank_mask:0xf
	s_nop 0
	v_readlane_b32 s0, v192, 0
	v_readlane_b32 s1, v192, 16
	v_readlane_b32 s6, v192, 32
	v_readlane_b32 s7, v192, 48
	s_nop 1
	v_mov_b32_e32 v193, s0
	v_add_f32_e32 v193, s1, v193
	v_add_f32_e32 v193, s6, v193
	v_add_f32_e32 v193, s7, v193
	v_fmamk_f32 v193, v193, 0x3a800000, v212
	v_rsq_f32_e32 v213, v193
	s_nop 0
	v_mul_f32_e32 v194, v64, v213
	v_mul_f32_e32 v195, v65, v213
	v_mul_f32_e32 v196, v66, v213
	v_mul_f32_e32 v197, v67, v213
	v_mul_f32_e32 v198, v68, v213
	v_mul_f32_e32 v199, v69, v213
	v_mul_f32_e32 v200, v70, v213
	v_mul_f32_e32 v201, v71, v213
	v_mul_f32_e32 v202, v72, v213
	v_mul_f32_e32 v203, v73, v213
	v_mul_f32_e32 v204, v74, v213
	v_mul_f32_e32 v205, v75, v213
	v_mul_f32_e32 v206, v76, v213
	v_mul_f32_e32 v207, v77, v213
	v_mul_f32_e32 v208, v78, v213
	v_mul_f32_e32 v209, v79, v213
	v_mul_f32_e32 v194, v128, v194
	v_mul_f32_e32 v195, v129, v195
	v_mul_f32_e32 v196, v130, v196
	v_mul_f32_e32 v197, v131, v197
	v_mul_f32_e32 v198, v132, v198
	v_mul_f32_e32 v199, v133, v199
	v_mul_f32_e32 v200, v134, v200
	v_mul_f32_e32 v201, v135, v201
	v_mul_f32_e32 v202, v136, v202
	v_mul_f32_e32 v203, v137, v203
	v_mul_f32_e32 v204, v138, v204
	v_mul_f32_e32 v205, v139, v205
	v_mul_f32_e32 v206, v140, v206
	v_mul_f32_e32 v207, v141, v207
	v_mul_f32_e32 v208, v142, v208
	v_mul_f32_e32 v209, v143, v209
	v_fma_f32 v194, v194, v160, v144
	v_fma_f32 v195, v195, v161, v145
	v_fma_f32 v196, v196, v162, v146
	v_fma_f32 v197, v197, v163, v147
	v_fma_f32 v198, v198, v164, v148
	v_fma_f32 v199, v199, v165, v149
	v_fma_f32 v200, v200, v166, v150
	v_fma_f32 v201, v201, v167, v151
	v_fma_f32 v202, v202, v168, v152
	v_fma_f32 v203, v203, v169, v153
	v_fma_f32 v204, v204, v170, v154
	v_fma_f32 v205, v205, v171, v155
	v_fma_f32 v206, v206, v172, v156
	v_fma_f32 v207, v207, v173, v157
	v_fma_f32 v208, v208, v174, v158
	v_fma_f32 v209, v209, v175, v159
	v_cvt_pk_bf16_f32 v194, v194, v195
	v_cvt_pk_bf16_f32 v195, v196, v197
	v_cvt_pk_bf16_f32 v196, v198, v199
	v_cvt_pk_bf16_f32 v197, v200, v201
	v_cvt_pk_bf16_f32 v198, v202, v203
	v_cvt_pk_bf16_f32 v199, v204, v205
	v_cvt_pk_bf16_f32 v200, v206, v207
	v_cvt_pk_bf16_f32 v201, v208, v209
	global_store_dwordx2 v211, v[194:195], s[24:25]
	global_store_dwordx2 v211, v[196:197], s[24:25] offset:512
	global_store_dwordx2 v211, v[198:199], s[24:25] offset:1024
	global_store_dwordx2 v211, v[200:201], s[24:25] offset:1536
	s_waitcnt vmcnt(8)
	v_lshlrev_b32_e32 v176, 16, v56
	v_and_b32_e32 v177, 0xffff0000, v56
	v_lshlrev_b32_e32 v178, 16, v57
	v_and_b32_e32 v179, 0xffff0000, v57
	v_lshlrev_b32_e32 v180, 16, v58
	v_and_b32_e32 v181, 0xffff0000, v58
	v_lshlrev_b32_e32 v182, 16, v59
	v_and_b32_e32 v183, 0xffff0000, v59
	v_lshlrev_b32_e32 v184, 16, v60
	v_and_b32_e32 v185, 0xffff0000, v60
	v_lshlrev_b32_e32 v186, 16, v61
	v_and_b32_e32 v187, 0xffff0000, v61
	v_lshlrev_b32_e32 v188, 16, v62
	v_and_b32_e32 v189, 0xffff0000, v62
	v_lshlrev_b32_e32 v190, 16, v63
	v_and_b32_e32 v191, 0xffff0000, v63
	v_mul_f32_e32 v192, v176, v176
	v_fmac_f32_e32 v192, v177, v177
	v_fmac_f32_e32 v192, v178, v178
	v_fmac_f32_e32 v192, v179, v179
	v_fmac_f32_e32 v192, v180, v180
	v_fmac_f32_e32 v192, v181, v181
	v_fmac_f32_e32 v192, v182, v182
	v_fmac_f32_e32 v192, v183, v183
	v_fmac_f32_e32 v192, v184, v184
	v_fmac_f32_e32 v192, v185, v185
	v_fmac_f32_e32 v192, v186, v186
	v_fmac_f32_e32 v192, v187, v187
	v_fmac_f32_e32 v192, v188, v188
	v_fmac_f32_e32 v192, v189, v189
	v_fmac_f32_e32 v192, v190, v190
	v_fmac_f32_e32 v192, v191, v191
	v_mul_f32_e32 v194, v112, v176
	v_mul_f32_e32 v195, v113, v177
	v_mul_f32_e32 v196, v114, v178
	v_mul_f32_e32 v197, v115, v179
	v_mul_f32_e32 v198, v116, v180
	v_mul_f32_e32 v199, v117, v181
	v_mul_f32_e32 v200, v118, v182
	v_mul_f32_e32 v201, v119, v183
	v_mul_f32_e32 v202, v120, v184
	v_mul_f32_e32 v203, v121, v185
	v_mul_f32_e32 v204, v122, v186
	v_mul_f32_e32 v205, v123, v187
	v_mul_f32_e32 v206, v124, v188
	v_mul_f32_e32 v207, v125, v189
	v_mul_f32_e32 v208, v126, v190
	v_mul_f32_e32 v209, v127, v191
	s_nop 1
	v_add_f32_dpp v193, v192, v192 quad_perm:[1,0,3,2] row_mask:0xf bank_mask:0xf
	s_nop 1
	v_add_f32_dpp v192, v193, v193 quad_perm:[2,3,0,1] row_mask:0xf bank_mask:0xf
	s_nop 1
	v_add_f32_dpp v193, v192, v192 row_half_mirror row_mask:0xf bank_mask:0xf
	s_nop 1
	v_add_f32_dpp v192, v193, v193 row_mirror row_mask:0xf bank_mask:0xf
	s_nop 0
	v_readlane_b32 s0, v192, 0
	v_readlane_b32 s1, v192, 16
	v_readlane_b32 s6, v192, 32
	v_readlane_b32 s7, v192, 48
	s_nop 1
	v_mov_b32_e32 v193, s0
	v_add_f32_e32 v193, s1, v193
	v_add_f32_e32 v193, s6, v193
	v_add_f32_e32 v193, s7, v193
	v_fmamk_f32 v193, v193, 0x3a800000, v212
	v_rsq_f32_e32 v213, v193
	s_nop 0
	v_mul_f32_e32 v194, v213, v194
	v_mul_f32_e32 v195, v213, v195
	v_mul_f32_e32 v196, v213, v196
	v_mul_f32_e32 v197, v213, v197
	v_mul_f32_e32 v198, v213, v198
	v_mul_f32_e32 v199, v213, v199
	v_mul_f32_e32 v200, v213, v200
	v_mul_f32_e32 v201, v213, v201
	v_mul_f32_e32 v202, v213, v202
	v_mul_f32_e32 v203, v213, v203
	v_mul_f32_e32 v204, v213, v204
	v_mul_f32_e32 v205, v213, v205
	v_mul_f32_e32 v206, v213, v206
	v_mul_f32_e32 v207, v213, v207
	v_mul_f32_e32 v208, v213, v208
	v_mul_f32_e32 v209, v213, v209
	v_fmac_f32_e32 v80, v96, v194
	v_fmac_f32_e32 v81, v97, v195
	v_fmac_f32_e32 v82, v98, v196
	v_fmac_f32_e32 v83, v99, v197
	v_fmac_f32_e32 v84, v100, v198
	v_fmac_f32_e32 v85, v101, v199
	v_fmac_f32_e32 v86, v102, v200
	v_fmac_f32_e32 v87, v103, v201
	v_fmac_f32_e32 v88, v104, v202
	v_fmac_f32_e32 v89, v105, v203
	v_fmac_f32_e32 v90, v106, v204
	v_fmac_f32_e32 v91, v107, v205
	v_fmac_f32_e32 v92, v108, v206
	v_fmac_f32_e32 v93, v109, v207
	v_fmac_f32_e32 v94, v110, v208
	v_fmac_f32_e32 v95, v111, v209
	global_store_dwordx4 v210, v[80:83], s[20:21] nt
	global_store_dwordx4 v210, v[84:87], s[20:21] offset:1024 nt
	global_store_dwordx4 v210, v[88:91], s[20:21] offset:2048 nt
	global_store_dwordx4 v210, v[92:95], s[20:21] offset:3072 nt
	v_mul_f32_e32 v192, v80, v80
	v_fmac_f32_e32 v192, v81, v81
	v_fmac_f32_e32 v192, v82, v82
	v_fmac_f32_e32 v192, v83, v83
	v_fmac_f32_e32 v192, v84, v84
	v_fmac_f32_e32 v192, v85, v85
	v_fmac_f32_e32 v192, v86, v86
	v_fmac_f32_e32 v192, v87, v87
	v_fmac_f32_e32 v192, v88, v88
	v_fmac_f32_e32 v192, v89, v89
	v_fmac_f32_e32 v192, v90, v90
	v_fmac_f32_e32 v192, v91, v91
	v_fmac_f32_e32 v192, v92, v92
	v_fmac_f32_e32 v192, v93, v93
	v_fmac_f32_e32 v192, v94, v94
	v_fmac_f32_e32 v192, v95, v95
	s_nop 1
	v_add_f32_dpp v193, v192, v192 quad_perm:[1,0,3,2] row_mask:0xf bank_mask:0xf
	s_nop 1
	v_add_f32_dpp v192, v193, v193 quad_perm:[2,3,0,1] row_mask:0xf bank_mask:0xf
	s_nop 1
	v_add_f32_dpp v193, v192, v192 row_half_mirror row_mask:0xf bank_mask:0xf
	s_nop 1
	v_add_f32_dpp v192, v193, v193 row_mirror row_mask:0xf bank_mask:0xf
	s_nop 0
	v_readlane_b32 s0, v192, 0
	v_readlane_b32 s1, v192, 16
	v_readlane_b32 s6, v192, 32
	v_readlane_b32 s7, v192, 48
	s_nop 1
	v_mov_b32_e32 v193, s0
	v_add_f32_e32 v193, s1, v193
	v_add_f32_e32 v193, s6, v193
	v_add_f32_e32 v193, s7, v193
	v_fmamk_f32 v193, v193, 0x3a800000, v212
	v_rsq_f32_e32 v213, v193
	s_nop 0
	v_mul_f32_e32 v194, v80, v213
	v_mul_f32_e32 v195, v81, v213
	v_mul_f32_e32 v196, v82, v213
	v_mul_f32_e32 v197, v83, v213
	v_mul_f32_e32 v198, v84, v213
	v_mul_f32_e32 v199, v85, v213
	v_mul_f32_e32 v200, v86, v213
	v_mul_f32_e32 v201, v87, v213
	v_mul_f32_e32 v202, v88, v213
	v_mul_f32_e32 v203, v89, v213
	v_mul_f32_e32 v204, v90, v213
	v_mul_f32_e32 v205, v91, v213
	v_mul_f32_e32 v206, v92, v213
	v_mul_f32_e32 v207, v93, v213
	v_mul_f32_e32 v208, v94, v213
	v_mul_f32_e32 v209, v95, v213
	v_mul_f32_e32 v194, v128, v194
	v_mul_f32_e32 v195, v129, v195
	v_mul_f32_e32 v196, v130, v196
	v_mul_f32_e32 v197, v131, v197
	v_mul_f32_e32 v198, v132, v198
	v_mul_f32_e32 v199, v133, v199
	v_mul_f32_e32 v200, v134, v200
	v_mul_f32_e32 v201, v135, v201
	v_mul_f32_e32 v202, v136, v202
	v_mul_f32_e32 v203, v137, v203
	v_mul_f32_e32 v204, v138, v204
	v_mul_f32_e32 v205, v139, v205
	v_mul_f32_e32 v206, v140, v206
	v_mul_f32_e32 v207, v141, v207
	v_mul_f32_e32 v208, v142, v208
	v_mul_f32_e32 v209, v143, v209
	v_fma_f32 v194, v194, v160, v144
	v_fma_f32 v195, v195, v161, v145
	v_fma_f32 v196, v196, v162, v146
	v_fma_f32 v197, v197, v163, v147
	v_fma_f32 v198, v198, v164, v148
	v_fma_f32 v199, v199, v165, v149
	v_fma_f32 v200, v200, v166, v150
	v_fma_f32 v201, v201, v167, v151
	v_fma_f32 v202, v202, v168, v152
	v_fma_f32 v203, v203, v169, v153
	v_fma_f32 v204, v204, v170, v154
	v_fma_f32 v205, v205, v171, v155
	v_fma_f32 v206, v206, v172, v156
	v_fma_f32 v207, v207, v173, v157
	v_fma_f32 v208, v208, v174, v158
	v_fma_f32 v209, v209, v175, v159
	v_cvt_pk_bf16_f32 v194, v194, v195
	v_cvt_pk_bf16_f32 v195, v196, v197
	v_cvt_pk_bf16_f32 v196, v198, v199
	v_cvt_pk_bf16_f32 v197, v200, v201
	v_cvt_pk_bf16_f32 v198, v202, v203
	v_cvt_pk_bf16_f32 v199, v204, v205
	v_cvt_pk_bf16_f32 v200, v206, v207
	v_cvt_pk_bf16_f32 v201, v208, v209
	global_store_dwordx2 v211, v[194:195], s[36:37]
	global_store_dwordx2 v211, v[196:197], s[36:37] offset:512
	global_store_dwordx2 v211, v[198:199], s[36:37] offset:1024
	global_store_dwordx2 v211, v[200:201], s[36:37] offset:1536
	s_add_u32 s18, s18, 0x400000
	s_addc_u32 s19, s19, 0
	s_add_u32 s20, s20, 0x400000
	s_addc_u32 s21, s21, 0
	s_add_u32 s24, s24, 0x200000
	s_addc_u32 s25, s25, 0
	s_add_u32 s36, s36, 0x200000
	s_addc_u32 s37, s37, 0
	s_branch .LBB0_313

.LBB0_377:
	s_and_b32 s4, s0, 0xffffe000
	s_and_b32 s5, s21, 0xfff
	s_or_b32 s4, s4, s5
	s_mul_hi_i32 s5, s4, 0x3000
	s_mulk_i32 s4, 0x3000
	s_add_u32 s4, s62, s4
	s_addc_u32 s5, s63, s5
	v_lshl_add_u64 v[6:7], v[0:1], 1, s[4:5]
	v_lshl_add_u64 v[8:9], v[6:7], 0, s[14:15]
	v_lshl_add_u64 v[4:5], v[6:7], 0, s[16:17]
	v_add_co_u32_e32 v6, vcc, s19, v6
	global_load_dwordx4 v[16:19], v[8:9], off offset:1024 nt
	global_load_dwordx4 v[20:23], v[4:5], off offset:1024 nt
	global_load_dwordx4 v[24:27], v[8:9], off offset:2048 nt
	global_load_dwordx4 v[28:31], v[4:5], off offset:2048 nt
	global_load_dwordx4 v[32:35], v[8:9], off offset:3072 nt
	global_load_dwordx4 v[36:39], v[4:5], off offset:3072 nt
	v_addc_co_u32_e32 v7, vcc, 0, v7, vcc
	global_load_dwordx4 v[40:43], v[6:7], off offset:-4096 nt
	global_load_dwordx4 v[44:47], v[6:7], off nt
	s_add_i32 s21, s21, s82
	s_add_i32 s0, s0, s1
	s_cmpk_lt_i32 s21, 0x4000
	s_waitcnt vmcnt(7)
	v_lshlrev_b32_e32 v48, 16, v19
	v_and_b32_e32 v49, 0xffff0000, v19
	v_lshlrev_b32_e32 v50, 16, v18
	v_and_b32_e32 v51, 0xffff0000, v18
	s_waitcnt vmcnt(6)
	v_lshlrev_b32_e32 v18, 16, v22
	v_and_b32_e32 v19, 0xffff0000, v22
	v_lshlrev_b32_e32 v8, 16, v17
	v_and_b32_e32 v9, 0xffff0000, v17
	v_lshlrev_b32_e32 v52, 16, v21
	v_and_b32_e32 v53, 0xffff0000, v21
	v_lshlrev_b32_e32 v54, 16, v16
	v_and_b32_e32 v55, 0xffff0000, v16
	v_lshlrev_b32_e32 v16, 16, v20
	v_and_b32_e32 v17, 0xffff0000, v20
	v_lshlrev_b32_e32 v20, 16, v23
	v_and_b32_e32 v21, 0xffff0000, v23
	s_waitcnt vmcnt(5)
	v_lshlrev_b32_e32 v22, 16, v27
	v_and_b32_e32 v23, 0xffff0000, v27
	v_lshlrev_b32_e32 v56, 16, v26
	v_and_b32_e32 v57, 0xffff0000, v26
	s_waitcnt vmcnt(4)
	v_lshlrev_b32_e32 v26, 16, v30
	v_and_b32_e32 v27, 0xffff0000, v30
	v_lshlrev_b32_e32 v58, 16, v25
	v_and_b32_e32 v59, 0xffff0000, v25
	v_lshlrev_b32_e32 v60, 16, v29
	v_and_b32_e32 v61, 0xffff0000, v29
	v_lshlrev_b32_e32 v62, 16, v24
	v_and_b32_e32 v63, 0xffff0000, v24
	v_lshlrev_b32_e32 v24, 16, v28
	v_and_b32_e32 v25, 0xffff0000, v28
	v_lshlrev_b32_e32 v28, 16, v31
	v_and_b32_e32 v29, 0xffff0000, v31
	s_waitcnt vmcnt(3)
	v_lshlrev_b32_e32 v30, 16, v35
	v_and_b32_e32 v31, 0xffff0000, v35
	v_lshlrev_b32_e32 v64, 16, v34
	v_and_b32_e32 v65, 0xffff0000, v34
	s_waitcnt vmcnt(2)
	v_lshlrev_b32_e32 v34, 16, v38
	v_and_b32_e32 v35, 0xffff0000, v38
	v_lshlrev_b32_e32 v68, 16, v37
	v_and_b32_e32 v69, 0xffff0000, v37
	v_lshlrev_b32_e32 v66, 16, v33
	v_and_b32_e32 v67, 0xffff0000, v33
	v_lshlrev_b32_e32 v70, 16, v32
	v_and_b32_e32 v71, 0xffff0000, v32
	v_lshlrev_b32_e32 v32, 16, v36
	v_and_b32_e32 v33, 0xffff0000, v36
	v_lshlrev_b32_e32 v36, 16, v39
	v_and_b32_e32 v37, 0xffff0000, v39
	s_waitcnt vmcnt(1)
	v_lshlrev_b32_e32 v38, 16, v43
	v_and_b32_e32 v39, 0xffff0000, v43
	v_lshlrev_b32_e32 v72, 16, v42
	v_and_b32_e32 v73, 0xffff0000, v42
	s_waitcnt vmcnt(0)
	v_lshlrev_b32_e32 v42, 16, v46
	v_and_b32_e32 v43, 0xffff0000, v46
	v_lshlrev_b32_e32 v74, 16, v41
	v_and_b32_e32 v75, 0xffff0000, v41
	v_lshlrev_b32_e32 v76, 16, v45
	v_and_b32_e32 v77, 0xffff0000, v45
	v_lshlrev_b32_e32 v78, 16, v40
	v_and_b32_e32 v79, 0xffff0000, v40
	v_lshlrev_b32_e32 v40, 16, v44
	v_and_b32_e32 v41, 0xffff0000, v44
	v_lshlrev_b32_e32 v44, 16, v47
	v_and_b32_e32 v45, 0xffff0000, v47
	v_mul_f32_e32 v102, 0xbfb8aa3b, v18
	v_mul_f32_e32 v103, 0xbfb8aa3b, v19
	v_mul_f32_e32 v104, 0xbfb8aa3b, v52
	v_mul_f32_e32 v105, 0xbfb8aa3b, v53
	v_mul_f32_e32 v108, 0xbfb8aa3b, v20
	v_mul_f32_e32 v109, 0xbfb8aa3b, v21
	v_mul_f32_e32 v110, 0xbfb8aa3b, v26
	v_mul_f32_e32 v111, 0xbfb8aa3b, v27
	v_mul_f32_e32 v112, 0xbfb8aa3b, v60
	v_mul_f32_e32 v113, 0xbfb8aa3b, v61
	v_mul_f32_e32 v116, 0xbfb8aa3b, v28
	v_mul_f32_e32 v117, 0xbfb8aa3b, v29
	v_mul_f32_e32 v118, 0xbfb8aa3b, v34
	v_mul_f32_e32 v119, 0xbfb8aa3b, v35
	v_mul_f32_e32 v120, 0xbfb8aa3b, v68
	v_mul_f32_e32 v121, 0xbfb8aa3b, v69
	v_mul_f32_e32 v124, 0xbfb8aa3b, v36
	v_mul_f32_e32 v125, 0xbfb8aa3b, v37
	v_mul_f32_e32 v126, 0xbfb8aa3b, v42
	v_mul_f32_e32 v127, 0xbfb8aa3b, v43
	v_mul_f32_e32 v128, 0xbfb8aa3b, v76
	v_mul_f32_e32 v129, 0xbfb8aa3b, v77
	v_mul_f32_e32 v132, 0xbfb8aa3b, v44
	v_mul_f32_e32 v133, 0xbfb8aa3b, v45
	v_exp_f32_e32 v102, v102
	v_exp_f32_e32 v103, v103
	v_exp_f32_e32 v104, v104
	v_exp_f32_e32 v105, v105
	v_exp_f32_e32 v108, v108
	v_exp_f32_e32 v109, v109
	v_exp_f32_e32 v110, v110
	v_exp_f32_e32 v111, v111
	v_exp_f32_e32 v112, v112
	v_exp_f32_e32 v113, v113
	v_exp_f32_e32 v116, v116
	v_exp_f32_e32 v117, v117
	v_exp_f32_e32 v118, v118
	v_exp_f32_e32 v119, v119
	v_exp_f32_e32 v120, v120
	v_exp_f32_e32 v121, v121
	v_mov_b32_e32 v80, v49
	v_mov_b32_e32 v81, v51
	v_mul_f32_e32 v106, 0xbfb8aa3b, v16
	v_mul_f32_e32 v107, 0xbfb8aa3b, v17
	v_mov_b32_e32 v86, v23
	v_mov_b32_e32 v87, v57
	v_mov_b32_e32 v92, v31
	v_mov_b32_e32 v93, v65
	v_mov_b32_e32 v98, v39
	v_mov_b32_e32 v99, v73
	v_exp_f32_e32 v124, v124
	v_exp_f32_e32 v125, v125
	v_exp_f32_e32 v126, v126
	v_exp_f32_e32 v127, v127
	v_exp_f32_e32 v128, v128
	v_exp_f32_e32 v129, v129
	v_exp_f32_e32 v132, v132
	v_exp_f32_e32 v133, v133
	v_mov_b32_e32 v46, v48
	v_mov_b32_e32 v47, v50
	v_mov_b32_e32 v84, v22
	v_mov_b32_e32 v85, v56
	v_mov_b32_e32 v90, v30
	v_mov_b32_e32 v91, v64
	v_mov_b32_e32 v96, v38
	v_mov_b32_e32 v97, v72
	v_pk_mul_f32 v[80:81], v[80:81], v[80:81]
	v_exp_f32_e32 v106, v106
	v_exp_f32_e32 v107, v107
	v_pk_mul_f32 v[86:87], v[86:87], v[86:87]
	v_pk_mul_f32 v[92:93], v[92:93], v[92:93]
	v_pk_mul_f32 v[98:99], v[98:99], v[98:99]
	v_pk_fma_f32 v[46:47], v[46:47], v[46:47], v[80:81]
	v_pk_fma_f32 v[80:81], v[84:85], v[84:85], v[86:87]
	v_pk_fma_f32 v[84:85], v[90:91], v[90:91], v[92:93]
	v_pk_fma_f32 v[86:87], v[96:97], v[96:97], v[98:99]
	v_mov_b32_e32 v90, v47
	v_mov_b32_e32 v92, v85
	v_mov_b32_e32 v93, v81
	v_mov_b32_e32 v85, v80
	v_mov_b32_e32 v91, v87
	v_mov_b32_e32 v47, v86
	v_add_f32_e32 v80, 1.0, v102
	v_add_f32_e32 v81, 1.0, v103
	v_add_f32_e32 v86, 1.0, v104
	v_add_f32_e32 v87, 1.0, v105
	v_add_f32_e32 v98, 1.0, v108
	v_add_f32_e32 v99, 1.0, v109
	v_add_f32_e32 v102, 1.0, v110
	v_add_f32_e32 v103, 1.0, v111
	v_add_f32_e32 v104, 1.0, v112
	v_add_f32_e32 v105, 1.0, v113
	v_add_f32_e32 v108, 1.0, v116
	v_add_f32_e32 v109, 1.0, v117
	v_add_f32_e32 v110, 1.0, v118
	v_add_f32_e32 v111, 1.0, v119
	v_add_f32_e32 v112, 1.0, v120
	v_add_f32_e32 v113, 1.0, v121
	v_add_f32_e32 v116, 1.0, v124
	v_add_f32_e32 v117, 1.0, v125
	v_add_f32_e32 v118, 1.0, v126
	v_add_f32_e32 v119, 1.0, v127
	v_add_f32_e32 v120, 1.0, v128
	v_add_f32_e32 v121, 1.0, v129
	v_add_f32_e32 v124, 1.0, v132
	v_add_f32_e32 v125, 1.0, v133
	v_rcp_f32_e32 v98, v98
	v_rcp_f32_e32 v99, v99
	v_rcp_f32_e32 v104, v104
	v_rcp_f32_e32 v105, v105
	v_rcp_f32_e32 v108, v108
	v_rcp_f32_e32 v109, v109
	v_rcp_f32_e32 v110, v110
	v_rcp_f32_e32 v111, v111
	v_rcp_f32_e32 v112, v112
	v_rcp_f32_e32 v113, v113
	v_add_f32_e32 v96, 1.0, v106
	v_add_f32_e32 v97, 1.0, v107
	v_rcp_f32_e32 v80, v80
	v_rcp_f32_e32 v81, v81
	v_rcp_f32_e32 v86, v86
	v_rcp_f32_e32 v87, v87
	v_rcp_f32_e32 v116, v116
	v_rcp_f32_e32 v117, v117
	v_rcp_f32_e32 v118, v118
	v_rcp_f32_e32 v119, v119
	v_rcp_f32_e32 v120, v120
	v_rcp_f32_e32 v121, v121
	v_rcp_f32_e32 v124, v124
	v_rcp_f32_e32 v125, v125
	v_rcp_f32_e32 v96, v96
	v_rcp_f32_e32 v97, v97
	v_rcp_f32_e32 v102, v102
	v_rcp_f32_e32 v103, v103
	v_pk_mul_f32 v[20:21], v[98:99], v[20:21]
	v_pk_mul_f32 v[60:61], v[104:105], v[60:61]
	v_pk_mul_f32 v[28:29], v[108:109], v[28:29]
	v_pk_mul_f32 v[34:35], v[110:111], v[34:35]
	v_pk_mul_f32 v[68:69], v[112:113], v[68:69]
	v_mov_b32_e32 v89, v58
	v_mov_b32_e32 v95, v66
	v_pk_mul_f32 v[18:19], v[80:81], v[18:19]
	v_pk_mul_f32 v[52:53], v[86:87], v[52:53]
	v_pk_mul_f32 v[36:37], v[116:117], v[36:37]
	v_pk_mul_f32 v[42:43], v[118:119], v[42:43]
	v_pk_mul_f32 v[76:77], v[120:121], v[76:77]
	v_pk_mul_f32 v[44:45], v[124:125], v[44:45]
	v_pk_mul_f32 v[20:21], v[20:21], v[48:49]
	v_pk_mul_f32 v[48:49], v[60:61], v[58:59]
	v_mov_b32_e32 v58, v63
	v_pk_mul_f32 v[22:23], v[28:29], v[22:23]
	v_pk_mul_f32 v[28:29], v[34:35], v[64:65]
	v_pk_mul_f32 v[34:35], v[68:69], v[66:67]
	v_mov_b32_e32 v66, v71
	v_mov_b32_e32 v83, v8
	v_mov_b32_e32 v88, v62
	v_mov_b32_e32 v94, v70
	v_mov_b32_e32 v101, v74
	v_pk_mul_f32 v[16:17], v[96:97], v[16:17]
	v_pk_mul_f32 v[18:19], v[18:19], v[50:51]
	v_pk_mul_f32 v[50:51], v[52:53], v[8:9]
	v_mov_b32_e32 v8, v55
	v_pk_mul_f32 v[30:31], v[36:37], v[30:31]
	v_pk_mul_f32 v[36:37], v[42:43], v[72:73]
	v_pk_mul_f32 v[42:43], v[76:77], v[74:75]
	v_mov_b32_e32 v74, v79
	v_pk_mul_f32 v[38:39], v[44:45], v[38:39]
	v_pk_mul_f32 v[44:45], v[58:59], v[58:59]
	v_pk_mul_f32 v[52:53], v[66:67], v[66:67]
	v_mov_b32_e32 v82, v54
	v_mov_b32_e32 v100, v78
	v_pk_mul_f32 v[16:17], v[16:17], v[54:55]
	v_pk_mul_f32 v[8:9], v[8:9], v[8:9]
	v_pk_mul_f32 v[54:55], v[74:75], v[74:75]
	v_pk_fma_f32 v[44:45], v[88:89], v[88:89], v[44:45]
	v_pk_fma_f32 v[52:53], v[94:95], v[94:95], v[52:53]
	v_pk_mul_f32 v[26:27], v[102:103], v[26:27]
	v_pk_fma_f32 v[8:9], v[82:83], v[82:83], v[8:9]
	v_pk_fma_f32 v[54:55], v[100:101], v[100:101], v[54:55]
	v_mov_b32_e32 v58, v52
	v_mov_b32_e32 v59, v44
	v_mov_b32_e32 v44, v53
	v_pk_mul_f32 v[26:27], v[26:27], v[56:57]
	v_mov_b32_e32 v56, v8
	v_mov_b32_e32 v57, v54
	v_mov_b32_e32 v54, v9
	v_pk_add_f32 v[8:9], v[58:59], v[44:45]
	v_pk_add_f32 v[44:45], v[56:57], v[54:55]
	v_pk_add_f32 v[8:9], v[92:93], v[8:9]
	v_pk_add_f32 v[44:45], v[90:91], v[44:45]
	v_pk_add_f32 v[8:9], v[84:85], v[8:9]
	v_pk_add_f32 v[44:45], v[46:47], v[44:45]
	ds_bpermute_b32 v47, v10, v9
	ds_bpermute_b32 v46, v10, v8
	ds_bpermute_b32 v53, v10, v45
	ds_bpermute_b32 v52, v10, v44
	v_mul_f32_e32 v114, 0xbfb8aa3b, v24
	v_mul_f32_e32 v115, 0xbfb8aa3b, v25
	s_waitcnt lgkmcnt(2)
	v_pk_add_f32 v[8:9], v[8:9], v[46:47]
	ds_bpermute_b32 v47, v11, v9
	s_waitcnt lgkmcnt(1)
	v_pk_add_f32 v[44:45], v[44:45], v[52:53]
	ds_bpermute_b32 v46, v11, v8
	ds_bpermute_b32 v53, v11, v45
	ds_bpermute_b32 v52, v11, v44
	v_mul_f32_e32 v122, 0xbfb8aa3b, v32
	v_mul_f32_e32 v123, 0xbfb8aa3b, v33
	s_waitcnt lgkmcnt(2)
	v_pk_add_f32 v[8:9], v[8:9], v[46:47]
	ds_bpermute_b32 v47, v12, v9
	s_waitcnt lgkmcnt(1)
	v_pk_add_f32 v[44:45], v[44:45], v[52:53]
	ds_bpermute_b32 v46, v12, v8
	ds_bpermute_b32 v53, v12, v45
	ds_bpermute_b32 v52, v12, v44
	v_mul_f32_e32 v130, 0xbfb8aa3b, v40
	v_mul_f32_e32 v131, 0xbfb8aa3b, v41
	s_waitcnt lgkmcnt(2)
	v_pk_add_f32 v[8:9], v[8:9], v[46:47]
	ds_bpermute_b32 v47, v13, v9
	s_waitcnt lgkmcnt(1)
	v_pk_add_f32 v[44:45], v[44:45], v[52:53]
	ds_bpermute_b32 v46, v13, v8
	ds_bpermute_b32 v53, v13, v45
	ds_bpermute_b32 v52, v13, v44
	v_exp_f32_e32 v114, v114
	v_exp_f32_e32 v115, v115
	s_waitcnt lgkmcnt(2)
	v_pk_add_f32 v[8:9], v[8:9], v[46:47]
	ds_bpermute_b32 v47, v14, v9
	s_waitcnt lgkmcnt(1)
	v_pk_add_f32 v[44:45], v[44:45], v[52:53]
	ds_bpermute_b32 v46, v14, v8
	ds_bpermute_b32 v53, v14, v45
	ds_bpermute_b32 v52, v14, v44
	v_exp_f32_e32 v122, v122
	v_exp_f32_e32 v123, v123
	s_waitcnt lgkmcnt(2)
	v_pk_add_f32 v[8:9], v[8:9], v[46:47]
	ds_bpermute_b32 v47, v15, v9
	s_waitcnt lgkmcnt(1)
	v_pk_add_f32 v[44:45], v[44:45], v[52:53]
	ds_bpermute_b32 v46, v15, v8
	ds_bpermute_b32 v53, v15, v45
	ds_bpermute_b32 v52, v15, v44
	v_exp_f32_e32 v130, v130
	v_exp_f32_e32 v131, v131
	s_waitcnt lgkmcnt(2)
	v_pk_add_f32 v[8:9], v[8:9], v[46:47]
	v_add_f32_e32 v106, 1.0, v114
	s_waitcnt lgkmcnt(0)
	v_pk_add_f32 v[44:45], v[44:45], v[52:53]
	v_pk_fma_f32 v[8:9], v[8:9], s[18:19], v[2:3] op_sel_hi:[1,0,0]
	v_pk_fma_f32 v[44:45], v[44:45], s[18:19], v[2:3] op_sel_hi:[1,0,0]
	v_mul_f32_e32 v46, 0x4b800000, v9
	v_cmp_gt_f32_e64 s[4:5], s20, v9
	v_add_f32_e32 v107, 1.0, v115
	v_mul_f32_e32 v47, 0x4b800000, v8
	v_cmp_gt_f32_e32 vcc, s20, v8
	v_mul_f32_e32 v52, 0x4b800000, v45
	v_mul_f32_e32 v53, 0x4b800000, v44
	v_cmp_gt_f32_e64 s[6:7], s20, v44
	v_cndmask_b32_e64 v9, v9, v46, s[4:5]
	v_cmp_gt_f32_e64 s[10:11], s20, v45
	v_add_f32_e32 v114, 1.0, v122
	v_add_f32_e32 v115, 1.0, v123
	v_add_f32_e32 v122, 1.0, v130
	v_add_f32_e32 v123, 1.0, v131
	v_rcp_f32_e32 v106, v106
	v_rcp_f32_e32 v107, v107
	v_cndmask_b32_e32 v8, v8, v47, vcc
	v_cndmask_b32_e64 v45, v45, v52, s[10:11]
	v_cndmask_b32_e64 v44, v44, v53, s[6:7]
	v_rsq_f32_e32 v9, v9
	v_rcp_f32_e32 v114, v114
	v_rcp_f32_e32 v115, v115
	v_rcp_f32_e32 v122, v122
	v_rcp_f32_e32 v123, v123
	v_rsq_f32_e32 v46, v8
	v_rsq_f32_e32 v45, v45
	v_rsq_f32_e32 v47, v44
	v_pk_mul_f32 v[24:25], v[106:107], v[24:25]
	v_mul_f32_e32 v8, 0x45800000, v9
	v_pk_mul_f32 v[32:33], v[114:115], v[32:33]
	v_pk_mul_f32 v[40:41], v[122:123], v[40:41]
	v_pk_mul_f32 v[24:25], v[24:25], v[62:63]
	v_mul_f32_e32 v44, 0x45800000, v46
	v_mul_f32_e32 v52, 0x45800000, v45
	v_mul_f32_e32 v53, 0x45800000, v47
	v_cndmask_b32_e64 v8, v9, v8, s[4:5]
	v_pk_mul_f32 v[32:33], v[32:33], v[70:71]
	v_pk_mul_f32 v[40:41], v[40:41], v[78:79]
	v_cndmask_b32_e32 v44, v46, v44, vcc
	v_cndmask_b32_e64 v46, v45, v52, s[10:11]
	v_cndmask_b32_e64 v52, v47, v53, s[6:7]
	v_pk_mul_f32 v[24:25], v[24:25], v[8:9] op_sel_hi:[1,0]
	v_pk_mul_f32 v[48:49], v[48:49], v[8:9] op_sel_hi:[1,0]
	v_pk_mul_f32 v[26:27], v[26:27], v[8:9] op_sel_hi:[1,0]
	v_pk_mul_f32 v[8:9], v[22:23], v[8:9] op_sel_hi:[1,0]
	v_pk_mul_f32 v[22:23], v[32:33], v[44:45] op_sel_hi:[1,0]
	v_pk_mul_f32 v[32:33], v[34:35], v[44:45] op_sel_hi:[1,0]
	v_pk_mul_f32 v[28:29], v[28:29], v[44:45] op_sel_hi:[1,0]
	v_pk_mul_f32 v[30:31], v[30:31], v[44:45] op_sel_hi:[1,0]
	v_pk_mul_f32 v[34:35], v[40:41], v[46:47] op_sel_hi:[1,0]
	v_pk_mul_f32 v[40:41], v[42:43], v[46:47] op_sel_hi:[1,0]
	v_pk_mul_f32 v[36:37], v[36:37], v[46:47] op_sel_hi:[1,0]
	v_pk_mul_f32 v[38:39], v[38:39], v[46:47] op_sel_hi:[1,0]
	v_pk_mul_f32 v[42:43], v[16:17], v[52:53] op_sel_hi:[1,0]
	v_pk_mul_f32 v[44:45], v[50:51], v[52:53] op_sel_hi:[1,0]
	v_pk_mul_f32 v[46:47], v[18:19], v[52:53] op_sel_hi:[1,0]
	v_pk_mul_f32 v[50:51], v[20:21], v[52:53] op_sel_hi:[1,0]
	v_cvt_pk_bf16_f32 v16, v24, v25
	v_cvt_pk_bf16_f32 v17, v48, v49
	v_cvt_pk_bf16_f32 v18, v26, v27
	v_cvt_pk_bf16_f32 v19, v8, v9
	v_cvt_pk_bf16_f32 v20, v22, v23
	v_cvt_pk_bf16_f32 v21, v32, v33
	v_cvt_pk_bf16_f32 v22, v28, v29
	v_cvt_pk_bf16_f32 v23, v30, v31
	v_cvt_pk_bf16_f32 v24, v34, v35
	v_cvt_pk_bf16_f32 v25, v40, v41
	v_cvt_pk_bf16_f32 v26, v36, v37
	v_cvt_pk_bf16_f32 v27, v38, v39
	v_cvt_pk_bf16_f32 v28, v42, v43
	v_cvt_pk_bf16_f32 v29, v44, v45
	v_cvt_pk_bf16_f32 v30, v46, v47
	v_cvt_pk_bf16_f32 v31, v50, v51
	global_store_dwordx4 v[4:5], v[16:19], off offset:2048
	global_store_dwordx4 v[4:5], v[20:23], off offset:3072
	global_store_dwordx4 v[6:7], v[24:27], off
	global_store_dwordx4 v[4:5], v[28:31], off offset:1024
	s_cbranch_scc1 .LBB0_377

.LBB0_395:
	s_and_b32 s6, s0, 0xffffe000
	s_and_b32 s7, s21, 0xfff
	s_or_b32 s6, s6, s7
	s_mul_hi_i32 s7, s6, 0x3000
	s_mulk_i32 s6, 0x3000
	s_add_u32 s6, s62, s6
	s_addc_u32 s7, s63, s7
	v_lshl_add_u64 v[6:7], v[0:1], 1, s[6:7]
	v_lshl_add_u64 v[8:9], v[6:7], 0, s[14:15]
	v_lshl_add_u64 v[4:5], v[6:7], 0, s[16:17]
	v_add_co_u32_e32 v6, vcc, s19, v6
	global_load_dwordx4 v[16:19], v[8:9], off offset:1024 nt
	global_load_dwordx4 v[20:23], v[4:5], off offset:1024 nt
	global_load_dwordx4 v[24:27], v[8:9], off offset:2048 nt
	global_load_dwordx4 v[28:31], v[4:5], off offset:2048 nt
	global_load_dwordx4 v[32:35], v[8:9], off offset:3072 nt
	global_load_dwordx4 v[36:39], v[4:5], off offset:3072 nt
	v_addc_co_u32_e32 v7, vcc, 0, v7, vcc
	global_load_dwordx4 v[40:43], v[6:7], off offset:-4096 nt
	global_load_dwordx4 v[44:47], v[6:7], off nt
	s_add_i32 s21, s21, s82
	s_add_i32 s0, s0, s1
	s_cmpk_lt_i32 s21, 0x4000
	s_waitcnt vmcnt(7)
	v_lshlrev_b32_e32 v48, 16, v19
	v_and_b32_e32 v49, 0xffff0000, v19
	v_lshlrev_b32_e32 v50, 16, v18
	v_and_b32_e32 v51, 0xffff0000, v18
	s_waitcnt vmcnt(6)
	v_lshlrev_b32_e32 v18, 16, v22
	v_and_b32_e32 v19, 0xffff0000, v22
	v_lshlrev_b32_e32 v8, 16, v17
	v_and_b32_e32 v9, 0xffff0000, v17
	v_lshlrev_b32_e32 v52, 16, v21
	v_and_b32_e32 v53, 0xffff0000, v21
	v_lshlrev_b32_e32 v54, 16, v16
	v_and_b32_e32 v55, 0xffff0000, v16
	v_lshlrev_b32_e32 v16, 16, v20
	v_and_b32_e32 v17, 0xffff0000, v20
	v_lshlrev_b32_e32 v20, 16, v23
	v_and_b32_e32 v21, 0xffff0000, v23
	s_waitcnt vmcnt(5)
	v_lshlrev_b32_e32 v22, 16, v27
	v_and_b32_e32 v23, 0xffff0000, v27
	v_lshlrev_b32_e32 v56, 16, v26
	v_and_b32_e32 v57, 0xffff0000, v26
	s_waitcnt vmcnt(4)
	v_lshlrev_b32_e32 v26, 16, v30
	v_and_b32_e32 v27, 0xffff0000, v30
	v_lshlrev_b32_e32 v58, 16, v25
	v_and_b32_e32 v59, 0xffff0000, v25
	v_lshlrev_b32_e32 v60, 16, v29
	v_and_b32_e32 v61, 0xffff0000, v29
	v_lshlrev_b32_e32 v62, 16, v24
	v_and_b32_e32 v63, 0xffff0000, v24
	v_lshlrev_b32_e32 v24, 16, v28
	v_and_b32_e32 v25, 0xffff0000, v28
	v_lshlrev_b32_e32 v28, 16, v31
	v_and_b32_e32 v29, 0xffff0000, v31
	s_waitcnt vmcnt(3)
	v_lshlrev_b32_e32 v30, 16, v35
	v_and_b32_e32 v31, 0xffff0000, v35
	v_lshlrev_b32_e32 v64, 16, v34
	v_and_b32_e32 v65, 0xffff0000, v34
	s_waitcnt vmcnt(2)
	v_lshlrev_b32_e32 v34, 16, v38
	v_and_b32_e32 v35, 0xffff0000, v38
	v_lshlrev_b32_e32 v68, 16, v37
	v_and_b32_e32 v69, 0xffff0000, v37
	v_lshlrev_b32_e32 v66, 16, v33
	v_and_b32_e32 v67, 0xffff0000, v33
	v_lshlrev_b32_e32 v70, 16, v32
	v_and_b32_e32 v71, 0xffff0000, v32
	v_lshlrev_b32_e32 v32, 16, v36
	v_and_b32_e32 v33, 0xffff0000, v36
	v_lshlrev_b32_e32 v36, 16, v39
	v_and_b32_e32 v37, 0xffff0000, v39
	s_waitcnt vmcnt(1)
	v_lshlrev_b32_e32 v38, 16, v43
	v_and_b32_e32 v39, 0xffff0000, v43
	v_lshlrev_b32_e32 v72, 16, v42
	v_and_b32_e32 v73, 0xffff0000, v42
	s_waitcnt vmcnt(0)
	v_lshlrev_b32_e32 v42, 16, v46
	v_and_b32_e32 v43, 0xffff0000, v46
	v_lshlrev_b32_e32 v74, 16, v41
	v_and_b32_e32 v75, 0xffff0000, v41
	v_lshlrev_b32_e32 v76, 16, v45
	v_and_b32_e32 v77, 0xffff0000, v45
	v_lshlrev_b32_e32 v78, 16, v40
	v_and_b32_e32 v79, 0xffff0000, v40
	v_lshlrev_b32_e32 v40, 16, v44
	v_and_b32_e32 v41, 0xffff0000, v44
	v_lshlrev_b32_e32 v44, 16, v47
	v_and_b32_e32 v45, 0xffff0000, v47
	v_mul_f32_e32 v102, 0xbfb8aa3b, v18
	v_mul_f32_e32 v103, 0xbfb8aa3b, v19
	v_mul_f32_e32 v104, 0xbfb8aa3b, v52
	v_mul_f32_e32 v105, 0xbfb8aa3b, v53
	v_mul_f32_e32 v108, 0xbfb8aa3b, v20
	v_mul_f32_e32 v109, 0xbfb8aa3b, v21
	v_mul_f32_e32 v110, 0xbfb8aa3b, v26
	v_mul_f32_e32 v111, 0xbfb8aa3b, v27
	v_mul_f32_e32 v112, 0xbfb8aa3b, v60
	v_mul_f32_e32 v113, 0xbfb8aa3b, v61
	v_mul_f32_e32 v116, 0xbfb8aa3b, v28
	v_mul_f32_e32 v117, 0xbfb8aa3b, v29
	v_mul_f32_e32 v118, 0xbfb8aa3b, v34
	v_mul_f32_e32 v119, 0xbfb8aa3b, v35
	v_mul_f32_e32 v120, 0xbfb8aa3b, v68
	v_mul_f32_e32 v121, 0xbfb8aa3b, v69
	v_mul_f32_e32 v124, 0xbfb8aa3b, v36
	v_mul_f32_e32 v125, 0xbfb8aa3b, v37
	v_mul_f32_e32 v126, 0xbfb8aa3b, v42
	v_mul_f32_e32 v127, 0xbfb8aa3b, v43
	v_mul_f32_e32 v128, 0xbfb8aa3b, v76
	v_mul_f32_e32 v129, 0xbfb8aa3b, v77
	v_mul_f32_e32 v132, 0xbfb8aa3b, v44
	v_mul_f32_e32 v133, 0xbfb8aa3b, v45
	v_exp_f32_e32 v102, v102
	v_exp_f32_e32 v103, v103
	v_exp_f32_e32 v104, v104
	v_exp_f32_e32 v105, v105
	v_exp_f32_e32 v108, v108
	v_exp_f32_e32 v109, v109
	v_exp_f32_e32 v110, v110
	v_exp_f32_e32 v111, v111
	v_exp_f32_e32 v112, v112
	v_exp_f32_e32 v113, v113
	v_exp_f32_e32 v116, v116
	v_exp_f32_e32 v117, v117
	v_exp_f32_e32 v118, v118
	v_exp_f32_e32 v119, v119
	v_exp_f32_e32 v120, v120
	v_exp_f32_e32 v121, v121
	v_mov_b32_e32 v80, v49
	v_mov_b32_e32 v81, v51
	v_mul_f32_e32 v106, 0xbfb8aa3b, v16
	v_mul_f32_e32 v107, 0xbfb8aa3b, v17
	v_mov_b32_e32 v86, v23
	v_mov_b32_e32 v87, v57
	v_mov_b32_e32 v92, v31
	v_mov_b32_e32 v93, v65
	v_mov_b32_e32 v98, v39
	v_mov_b32_e32 v99, v73
	v_exp_f32_e32 v124, v124
	v_exp_f32_e32 v125, v125
	v_exp_f32_e32 v126, v126
	v_exp_f32_e32 v127, v127
	v_exp_f32_e32 v128, v128
	v_exp_f32_e32 v129, v129
	v_exp_f32_e32 v132, v132
	v_exp_f32_e32 v133, v133
	v_mov_b32_e32 v46, v48
	v_mov_b32_e32 v47, v50
	v_mov_b32_e32 v84, v22
	v_mov_b32_e32 v85, v56
	v_mov_b32_e32 v90, v30
	v_mov_b32_e32 v91, v64
	v_mov_b32_e32 v96, v38
	v_mov_b32_e32 v97, v72
	v_pk_mul_f32 v[80:81], v[80:81], v[80:81]
	v_exp_f32_e32 v106, v106
	v_exp_f32_e32 v107, v107
	v_pk_mul_f32 v[86:87], v[86:87], v[86:87]
	v_pk_mul_f32 v[92:93], v[92:93], v[92:93]
	v_pk_mul_f32 v[98:99], v[98:99], v[98:99]
	v_pk_fma_f32 v[46:47], v[46:47], v[46:47], v[80:81]
	v_pk_fma_f32 v[80:81], v[84:85], v[84:85], v[86:87]
	v_pk_fma_f32 v[84:85], v[90:91], v[90:91], v[92:93]
	v_pk_fma_f32 v[86:87], v[96:97], v[96:97], v[98:99]
	v_mov_b32_e32 v90, v47
	v_mov_b32_e32 v92, v85
	v_mov_b32_e32 v93, v81
	v_mov_b32_e32 v85, v80
	v_mov_b32_e32 v91, v87
	v_mov_b32_e32 v47, v86
	v_add_f32_e32 v80, 1.0, v102
	v_add_f32_e32 v81, 1.0, v103
	v_add_f32_e32 v86, 1.0, v104
	v_add_f32_e32 v87, 1.0, v105
	v_add_f32_e32 v98, 1.0, v108
	v_add_f32_e32 v99, 1.0, v109
	v_add_f32_e32 v102, 1.0, v110
	v_add_f32_e32 v103, 1.0, v111
	v_add_f32_e32 v104, 1.0, v112
	v_add_f32_e32 v105, 1.0, v113
	v_add_f32_e32 v108, 1.0, v116
	v_add_f32_e32 v109, 1.0, v117
	v_add_f32_e32 v110, 1.0, v118
	v_add_f32_e32 v111, 1.0, v119
	v_add_f32_e32 v112, 1.0, v120
	v_add_f32_e32 v113, 1.0, v121
	v_add_f32_e32 v116, 1.0, v124
	v_add_f32_e32 v117, 1.0, v125
	v_add_f32_e32 v118, 1.0, v126
	v_add_f32_e32 v119, 1.0, v127
	v_add_f32_e32 v120, 1.0, v128
	v_add_f32_e32 v121, 1.0, v129
	v_add_f32_e32 v124, 1.0, v132
	v_add_f32_e32 v125, 1.0, v133
	v_rcp_f32_e32 v98, v98
	v_rcp_f32_e32 v99, v99
	v_rcp_f32_e32 v104, v104
	v_rcp_f32_e32 v105, v105
	v_rcp_f32_e32 v108, v108
	v_rcp_f32_e32 v109, v109
	v_rcp_f32_e32 v110, v110
	v_rcp_f32_e32 v111, v111
	v_rcp_f32_e32 v112, v112
	v_rcp_f32_e32 v113, v113
	v_add_f32_e32 v96, 1.0, v106
	v_add_f32_e32 v97, 1.0, v107
	v_rcp_f32_e32 v80, v80
	v_rcp_f32_e32 v81, v81
	v_rcp_f32_e32 v86, v86
	v_rcp_f32_e32 v87, v87
	v_rcp_f32_e32 v116, v116
	v_rcp_f32_e32 v117, v117
	v_rcp_f32_e32 v118, v118
	v_rcp_f32_e32 v119, v119
	v_rcp_f32_e32 v120, v120
	v_rcp_f32_e32 v121, v121
	v_rcp_f32_e32 v124, v124
	v_rcp_f32_e32 v125, v125
	v_rcp_f32_e32 v96, v96
	v_rcp_f32_e32 v97, v97
	v_rcp_f32_e32 v102, v102
	v_rcp_f32_e32 v103, v103
	v_pk_mul_f32 v[20:21], v[98:99], v[20:21]
	v_pk_mul_f32 v[60:61], v[104:105], v[60:61]
	v_pk_mul_f32 v[28:29], v[108:109], v[28:29]
	v_pk_mul_f32 v[34:35], v[110:111], v[34:35]
	v_pk_mul_f32 v[68:69], v[112:113], v[68:69]
	v_mov_b32_e32 v89, v58
	v_mov_b32_e32 v95, v66
	v_pk_mul_f32 v[18:19], v[80:81], v[18:19]
	v_pk_mul_f32 v[52:53], v[86:87], v[52:53]
	v_pk_mul_f32 v[36:37], v[116:117], v[36:37]
	v_pk_mul_f32 v[42:43], v[118:119], v[42:43]
	v_pk_mul_f32 v[76:77], v[120:121], v[76:77]
	v_pk_mul_f32 v[44:45], v[124:125], v[44:45]
	v_pk_mul_f32 v[20:21], v[20:21], v[48:49]
	v_pk_mul_f32 v[48:49], v[60:61], v[58:59]
	v_mov_b32_e32 v58, v63
	v_pk_mul_f32 v[22:23], v[28:29], v[22:23]
	v_pk_mul_f32 v[28:29], v[34:35], v[64:65]
	v_pk_mul_f32 v[34:35], v[68:69], v[66:67]
	v_mov_b32_e32 v66, v71
	v_mov_b32_e32 v83, v8
	v_mov_b32_e32 v88, v62
	v_mov_b32_e32 v94, v70
	v_mov_b32_e32 v101, v74
	v_pk_mul_f32 v[16:17], v[96:97], v[16:17]
	v_pk_mul_f32 v[18:19], v[18:19], v[50:51]
	v_pk_mul_f32 v[50:51], v[52:53], v[8:9]
	v_mov_b32_e32 v8, v55
	v_pk_mul_f32 v[30:31], v[36:37], v[30:31]
	v_pk_mul_f32 v[36:37], v[42:43], v[72:73]
	v_pk_mul_f32 v[42:43], v[76:77], v[74:75]
	v_mov_b32_e32 v74, v79
	v_pk_mul_f32 v[38:39], v[44:45], v[38:39]
	v_pk_mul_f32 v[44:45], v[58:59], v[58:59]
	v_pk_mul_f32 v[52:53], v[66:67], v[66:67]
	v_mov_b32_e32 v82, v54
	v_mov_b32_e32 v100, v78
	v_pk_mul_f32 v[16:17], v[16:17], v[54:55]
	v_pk_mul_f32 v[8:9], v[8:9], v[8:9]
	v_pk_mul_f32 v[54:55], v[74:75], v[74:75]
	v_pk_fma_f32 v[44:45], v[88:89], v[88:89], v[44:45]
	v_pk_fma_f32 v[52:53], v[94:95], v[94:95], v[52:53]
	v_pk_mul_f32 v[26:27], v[102:103], v[26:27]
	v_pk_fma_f32 v[8:9], v[82:83], v[82:83], v[8:9]
	v_pk_fma_f32 v[54:55], v[100:101], v[100:101], v[54:55]
	v_mov_b32_e32 v58, v52
	v_mov_b32_e32 v59, v44
	v_mov_b32_e32 v44, v53
	v_pk_mul_f32 v[26:27], v[26:27], v[56:57]
	v_mov_b32_e32 v56, v8
	v_mov_b32_e32 v57, v54
	v_mov_b32_e32 v54, v9
	v_pk_add_f32 v[8:9], v[58:59], v[44:45]
	v_pk_add_f32 v[44:45], v[56:57], v[54:55]
	v_pk_add_f32 v[8:9], v[92:93], v[8:9]
	v_pk_add_f32 v[44:45], v[90:91], v[44:45]
	v_pk_add_f32 v[8:9], v[84:85], v[8:9]
	v_pk_add_f32 v[44:45], v[46:47], v[44:45]
	ds_bpermute_b32 v47, v10, v9
	ds_bpermute_b32 v46, v10, v8
	ds_bpermute_b32 v53, v10, v45
	ds_bpermute_b32 v52, v10, v44
	v_mul_f32_e32 v114, 0xbfb8aa3b, v24
	v_mul_f32_e32 v115, 0xbfb8aa3b, v25
	s_waitcnt lgkmcnt(2)
	v_pk_add_f32 v[8:9], v[8:9], v[46:47]
	ds_bpermute_b32 v47, v11, v9
	s_waitcnt lgkmcnt(1)
	v_pk_add_f32 v[44:45], v[44:45], v[52:53]
	ds_bpermute_b32 v46, v11, v8
	ds_bpermute_b32 v53, v11, v45
	ds_bpermute_b32 v52, v11, v44
	v_mul_f32_e32 v122, 0xbfb8aa3b, v32
	v_mul_f32_e32 v123, 0xbfb8aa3b, v33
	s_waitcnt lgkmcnt(2)
	v_pk_add_f32 v[8:9], v[8:9], v[46:47]
	ds_bpermute_b32 v47, v12, v9
	s_waitcnt lgkmcnt(1)
	v_pk_add_f32 v[44:45], v[44:45], v[52:53]
	ds_bpermute_b32 v46, v12, v8
	ds_bpermute_b32 v53, v12, v45
	ds_bpermute_b32 v52, v12, v44
	v_mul_f32_e32 v130, 0xbfb8aa3b, v40
	v_mul_f32_e32 v131, 0xbfb8aa3b, v41
	s_waitcnt lgkmcnt(2)
	v_pk_add_f32 v[8:9], v[8:9], v[46:47]
	ds_bpermute_b32 v47, v13, v9
	s_waitcnt lgkmcnt(1)
	v_pk_add_f32 v[44:45], v[44:45], v[52:53]
	ds_bpermute_b32 v46, v13, v8
	ds_bpermute_b32 v53, v13, v45
	ds_bpermute_b32 v52, v13, v44
	v_exp_f32_e32 v114, v114
	v_exp_f32_e32 v115, v115
	s_waitcnt lgkmcnt(2)
	v_pk_add_f32 v[8:9], v[8:9], v[46:47]
	ds_bpermute_b32 v47, v14, v9
	s_waitcnt lgkmcnt(1)
	v_pk_add_f32 v[44:45], v[44:45], v[52:53]
	ds_bpermute_b32 v46, v14, v8
	ds_bpermute_b32 v53, v14, v45
	ds_bpermute_b32 v52, v14, v44
	v_exp_f32_e32 v122, v122
	v_exp_f32_e32 v123, v123
	s_waitcnt lgkmcnt(2)
	v_pk_add_f32 v[8:9], v[8:9], v[46:47]
	ds_bpermute_b32 v47, v15, v9
	s_waitcnt lgkmcnt(1)
	v_pk_add_f32 v[44:45], v[44:45], v[52:53]
	ds_bpermute_b32 v46, v15, v8
	ds_bpermute_b32 v53, v15, v45
	ds_bpermute_b32 v52, v15, v44
	v_exp_f32_e32 v130, v130
	v_exp_f32_e32 v131, v131
	s_waitcnt lgkmcnt(2)
	v_pk_add_f32 v[8:9], v[8:9], v[46:47]
	v_add_f32_e32 v106, 1.0, v114
	s_waitcnt lgkmcnt(0)
	v_pk_add_f32 v[44:45], v[44:45], v[52:53]
	v_pk_fma_f32 v[8:9], v[8:9], s[18:19], v[2:3] op_sel_hi:[1,0,0]
	v_pk_fma_f32 v[44:45], v[44:45], s[18:19], v[2:3] op_sel_hi:[1,0,0]
	v_mul_f32_e32 v46, 0x4b800000, v9
	v_cmp_gt_f32_e64 s[6:7], s20, v9
	v_add_f32_e32 v107, 1.0, v115
	v_mul_f32_e32 v47, 0x4b800000, v8
	v_cmp_gt_f32_e32 vcc, s20, v8
	v_mul_f32_e32 v52, 0x4b800000, v45
	v_mul_f32_e32 v53, 0x4b800000, v44
	v_cmp_gt_f32_e64 s[10:11], s20, v44
	v_cndmask_b32_e64 v9, v9, v46, s[6:7]
	v_cmp_gt_f32_e64 s[12:13], s20, v45
	v_add_f32_e32 v114, 1.0, v122
	v_add_f32_e32 v115, 1.0, v123
	v_add_f32_e32 v122, 1.0, v130
	v_add_f32_e32 v123, 1.0, v131
	v_rcp_f32_e32 v106, v106
	v_rcp_f32_e32 v107, v107
	v_cndmask_b32_e32 v8, v8, v47, vcc
	v_cndmask_b32_e64 v45, v45, v52, s[12:13]
	v_cndmask_b32_e64 v44, v44, v53, s[10:11]
	v_rsq_f32_e32 v9, v9
	v_rcp_f32_e32 v114, v114
	v_rcp_f32_e32 v115, v115
	v_rcp_f32_e32 v122, v122
	v_rcp_f32_e32 v123, v123
	v_rsq_f32_e32 v46, v8
	v_rsq_f32_e32 v45, v45
	v_rsq_f32_e32 v47, v44
	v_pk_mul_f32 v[24:25], v[106:107], v[24:25]
	v_mul_f32_e32 v8, 0x45800000, v9
	v_pk_mul_f32 v[32:33], v[114:115], v[32:33]
	v_pk_mul_f32 v[40:41], v[122:123], v[40:41]
	v_pk_mul_f32 v[24:25], v[24:25], v[62:63]
	v_mul_f32_e32 v44, 0x45800000, v46
	v_mul_f32_e32 v52, 0x45800000, v45
	v_mul_f32_e32 v53, 0x45800000, v47
	v_cndmask_b32_e64 v8, v9, v8, s[6:7]
	v_pk_mul_f32 v[32:33], v[32:33], v[70:71]
	v_pk_mul_f32 v[40:41], v[40:41], v[78:79]
	v_cndmask_b32_e32 v44, v46, v44, vcc
	v_cndmask_b32_e64 v46, v45, v52, s[12:13]
	v_cndmask_b32_e64 v52, v47, v53, s[10:11]
	v_pk_mul_f32 v[24:25], v[24:25], v[8:9] op_sel_hi:[1,0]
	v_pk_mul_f32 v[48:49], v[48:49], v[8:9] op_sel_hi:[1,0]
	v_pk_mul_f32 v[26:27], v[26:27], v[8:9] op_sel_hi:[1,0]
	v_pk_mul_f32 v[8:9], v[22:23], v[8:9] op_sel_hi:[1,0]
	v_pk_mul_f32 v[22:23], v[32:33], v[44:45] op_sel_hi:[1,0]
	v_pk_mul_f32 v[32:33], v[34:35], v[44:45] op_sel_hi:[1,0]
	v_pk_mul_f32 v[28:29], v[28:29], v[44:45] op_sel_hi:[1,0]
	v_pk_mul_f32 v[30:31], v[30:31], v[44:45] op_sel_hi:[1,0]
	v_pk_mul_f32 v[34:35], v[40:41], v[46:47] op_sel_hi:[1,0]
	v_pk_mul_f32 v[40:41], v[42:43], v[46:47] op_sel_hi:[1,0]
	v_pk_mul_f32 v[36:37], v[36:37], v[46:47] op_sel_hi:[1,0]
	v_pk_mul_f32 v[38:39], v[38:39], v[46:47] op_sel_hi:[1,0]
	v_pk_mul_f32 v[42:43], v[16:17], v[52:53] op_sel_hi:[1,0]
	v_pk_mul_f32 v[44:45], v[50:51], v[52:53] op_sel_hi:[1,0]
	v_pk_mul_f32 v[46:47], v[18:19], v[52:53] op_sel_hi:[1,0]
	v_pk_mul_f32 v[50:51], v[20:21], v[52:53] op_sel_hi:[1,0]
	v_cvt_pk_bf16_f32 v16, v24, v25
	v_cvt_pk_bf16_f32 v17, v48, v49
	v_cvt_pk_bf16_f32 v18, v26, v27
	v_cvt_pk_bf16_f32 v19, v8, v9
	v_cvt_pk_bf16_f32 v20, v22, v23
	v_cvt_pk_bf16_f32 v21, v32, v33
	v_cvt_pk_bf16_f32 v22, v28, v29
	v_cvt_pk_bf16_f32 v23, v30, v31
	v_cvt_pk_bf16_f32 v24, v34, v35
	v_cvt_pk_bf16_f32 v25, v40, v41
	v_cvt_pk_bf16_f32 v26, v36, v37
	v_cvt_pk_bf16_f32 v27, v38, v39
	v_cvt_pk_bf16_f32 v28, v42, v43
	v_cvt_pk_bf16_f32 v29, v44, v45
	v_cvt_pk_bf16_f32 v30, v46, v47
	v_cvt_pk_bf16_f32 v31, v50, v51
	global_store_dwordx4 v[4:5], v[16:19], off offset:2048
	global_store_dwordx4 v[4:5], v[20:23], off offset:3072
	global_store_dwordx4 v[6:7], v[24:27], off
	global_store_dwordx4 v[4:5], v[28:31], off offset:1024
	s_cbranch_scc1 .LBB0_395

.LBB0_406:
	s_and_b32 s6, s19, 0xffffe000
	s_and_b32 s7, s23, 0xfff
	s_or_b32 s6, s7, s6
	s_bitset1_b32 s6, 12
	s_mul_hi_i32 s7, s6, 0x3000
	s_mulk_i32 s6, 0x3000
	s_add_u32 s6, s62, s6
	s_addc_u32 s7, s63, s7
	v_lshl_add_u64 v[0:1], s[6:7], 0, v[32:33]
	v_add_co_u32_e32 v38, vcc, s21, v0
	v_lshl_add_u64 v[12:13], v[0:1], 0, s[14:15]
	s_nop 0
	v_addc_co_u32_e32 v39, vcc, 0, v1, vcc
	s_cmpk_lt_i32 s23, 0x2000
	v_lshl_add_u64 v[36:37], v[0:1], 0, s[16:17]
	global_load_dwordx4 v[0:3], v[38:39], off offset:-4096 nt
	global_load_dwordx4 v[4:7], v[12:13], off offset:1024 nt
	global_load_dwordx4 v[8:11], v[12:13], off offset:2048 nt
	global_load_dwordx4 v[28:31], v[12:13], off offset:3072 nt
	global_load_dwordx4 v[24:27], v[38:39], off nt
	global_load_dwordx4 v[20:23], v[36:37], off offset:1024 nt
	global_load_dwordx4 v[16:19], v[36:37], off offset:2048 nt
	s_nop 0
	global_load_dwordx4 v[12:15], v[36:37], off offset:3072 nt
	s_cselect_b32 s7, s61, s44
	s_cselect_b32 s6, s60, s27
	s_and_b32 s10, s0, 0x1fff000
	s_add_u32 s6, s6, s10
	s_addc_u32 s7, s7, 0
	v_lshl_add_u64 v[40:41], s[6:7], 0, v[32:33]
	global_load_dwordx4 v[48:51], v[40:41], off nt
	global_load_dwordx4 v[52:55], v[40:41], off offset:1024 nt
	global_load_dwordx4 v[56:59], v[40:41], off offset:2048 nt
	global_load_dwordx4 v[60:63], v[40:41], off offset:3072 nt
	s_add_i32 s19, s19, s20
	s_add_i32 s23, s23, s82
	s_add_i32 s0, s0, s1
	s_cmpk_lt_i32 s23, 0x4000
	s_waitcnt vmcnt(11)
	v_lshlrev_b32_e32 v68, 16, v2
	v_and_b32_e32 v69, 0xffff0000, v2
	v_lshlrev_b32_e32 v70, 16, v3
	v_and_b32_e32 v71, 0xffff0000, v3
	s_waitcnt vmcnt(9)
	v_lshlrev_b32_e32 v84, 16, v10
	v_and_b32_e32 v85, 0xffff0000, v10
	v_lshlrev_b32_e32 v86, 16, v11
	v_and_b32_e32 v87, 0xffff0000, v11
	s_waitcnt vmcnt(7)
	v_lshlrev_b32_e32 v2, 16, v25
	v_and_b32_e32 v3, 0xffff0000, v25
	s_waitcnt vmcnt(6)
	v_lshlrev_b32_e32 v10, 16, v21
	v_and_b32_e32 v11, 0xffff0000, v21
	v_lshlrev_b32_e32 v64, 16, v0
	v_and_b32_e32 v65, 0xffff0000, v0
	v_lshlrev_b32_e32 v66, 16, v1
	v_and_b32_e32 v67, 0xffff0000, v1
	v_lshlrev_b32_e32 v72, 16, v4
	v_and_b32_e32 v73, 0xffff0000, v4
	v_lshlrev_b32_e32 v74, 16, v5
	v_and_b32_e32 v75, 0xffff0000, v5
	v_lshlrev_b32_e32 v76, 16, v6
	v_and_b32_e32 v77, 0xffff0000, v6
	v_lshlrev_b32_e32 v78, 16, v7
	v_and_b32_e32 v79, 0xffff0000, v7
	v_lshlrev_b32_e32 v80, 16, v8
	v_and_b32_e32 v81, 0xffff0000, v8
	v_lshlrev_b32_e32 v82, 16, v9
	v_and_b32_e32 v83, 0xffff0000, v9
	v_lshlrev_b32_e32 v88, 16, v28
	v_and_b32_e32 v89, 0xffff0000, v28
	v_lshlrev_b32_e32 v90, 16, v29
	v_and_b32_e32 v91, 0xffff0000, v29
	v_lshlrev_b32_e32 v92, 16, v30
	v_and_b32_e32 v93, 0xffff0000, v30
	v_lshlrev_b32_e32 v94, 16, v31
	v_and_b32_e32 v95, 0xffff0000, v31
	v_lshlrev_b32_e32 v0, 16, v26
	v_and_b32_e32 v1, 0xffff0000, v26
	v_lshlrev_b32_e32 v4, 16, v24
	v_and_b32_e32 v5, 0xffff0000, v24
	v_lshlrev_b32_e32 v6, 16, v27
	v_and_b32_e32 v7, 0xffff0000, v27
	v_lshlrev_b32_e32 v8, 16, v22
	v_and_b32_e32 v9, 0xffff0000, v22
	v_lshlrev_b32_e32 v24, 16, v20
	v_and_b32_e32 v25, 0xffff0000, v20
	v_lshlrev_b32_e32 v20, 16, v23
	v_and_b32_e32 v21, 0xffff0000, v23
	s_waitcnt vmcnt(5)
	v_lshlrev_b32_e32 v22, 16, v18
	v_and_b32_e32 v23, 0xffff0000, v18
	v_lshlrev_b32_e32 v26, 16, v17
	v_and_b32_e32 v27, 0xffff0000, v17
	v_lshlrev_b32_e32 v28, 16, v16
	v_and_b32_e32 v29, 0xffff0000, v16
	v_lshlrev_b32_e32 v16, 16, v19
	v_and_b32_e32 v17, 0xffff0000, v19
	s_waitcnt vmcnt(4)
	v_lshlrev_b32_e32 v18, 16, v14
	v_and_b32_e32 v19, 0xffff0000, v14
	v_lshlrev_b32_e32 v30, 16, v13
	v_and_b32_e32 v31, 0xffff0000, v13
	v_lshlrev_b32_e32 v40, 16, v12
	v_and_b32_e32 v41, 0xffff0000, v12
	v_mul_f32_e32 v96, 0xbfb8aa3b, v2
	v_mul_f32_e32 v97, 0xbfb8aa3b, v3
	v_mul_f32_e32 v104, 0xbfb8aa3b, v10
	v_mul_f32_e32 v105, 0xbfb8aa3b, v11
	v_lshlrev_b32_e32 v12, 16, v15
	v_and_b32_e32 v13, 0xffff0000, v15
	v_mul_f32_e32 v14, 0xbfb8aa3b, v0
	v_mul_f32_e32 v15, 0xbfb8aa3b, v1
	v_mul_f32_e32 v98, 0xbfb8aa3b, v4
	v_mul_f32_e32 v99, 0xbfb8aa3b, v5
	v_mul_f32_e32 v100, 0xbfb8aa3b, v6
	v_mul_f32_e32 v101, 0xbfb8aa3b, v7
	v_mul_f32_e32 v102, 0xbfb8aa3b, v8
	v_mul_f32_e32 v103, 0xbfb8aa3b, v9
	v_mul_f32_e32 v106, 0xbfb8aa3b, v24
	v_mul_f32_e32 v107, 0xbfb8aa3b, v25
	v_mul_f32_e32 v112, 0xbfb8aa3b, v26
	v_mul_f32_e32 v113, 0xbfb8aa3b, v27
	v_mul_f32_e32 v114, 0xbfb8aa3b, v28
	v_mul_f32_e32 v115, 0xbfb8aa3b, v29
	v_mul_f32_e32 v118, 0xbfb8aa3b, v18
	v_mul_f32_e32 v119, 0xbfb8aa3b, v19
	v_mul_f32_e32 v120, 0xbfb8aa3b, v30
	v_mul_f32_e32 v121, 0xbfb8aa3b, v31
	v_mul_f32_e32 v122, 0xbfb8aa3b, v40
	v_mul_f32_e32 v123, 0xbfb8aa3b, v41
	v_exp_f32_e32 v128, v96
	v_exp_f32_e32 v129, v97
	v_exp_f32_e32 v136, v104
	v_exp_f32_e32 v137, v105
	v_mul_f32_e32 v116, 0xbfb8aa3b, v16
	v_mul_f32_e32 v117, 0xbfb8aa3b, v17
	v_mul_f32_e32 v124, 0xbfb8aa3b, v12
	v_mul_f32_e32 v125, 0xbfb8aa3b, v13
	v_exp_f32_e32 v126, v14
	v_exp_f32_e32 v127, v15
	v_exp_f32_e32 v130, v98
	v_exp_f32_e32 v131, v99
	v_exp_f32_e32 v132, v100
	v_exp_f32_e32 v133, v101
	v_exp_f32_e32 v134, v102
	v_exp_f32_e32 v135, v103
	v_exp_f32_e32 v138, v106
	v_exp_f32_e32 v139, v107
	v_exp_f32_e32 v112, v112
	v_exp_f32_e32 v113, v113
	v_exp_f32_e32 v114, v114
	v_exp_f32_e32 v115, v115
	v_exp_f32_e32 v118, v118
	v_exp_f32_e32 v119, v119
	v_exp_f32_e32 v120, v120
	v_exp_f32_e32 v121, v121
	v_exp_f32_e32 v122, v122
	v_exp_f32_e32 v123, v123
	v_exp_f32_e32 v116, v116
	v_exp_f32_e32 v117, v117
	v_exp_f32_e32 v124, v124
	v_exp_f32_e32 v125, v125
	s_waitcnt vmcnt(3)
	v_lshlrev_b32_e32 v14, 16, v48
	v_and_b32_e32 v15, 0xffff0000, v48
	v_lshlrev_b32_e32 v48, 16, v49
	v_and_b32_e32 v49, 0xffff0000, v49
	s_waitcnt vmcnt(2)
	v_lshlrev_b32_e32 v98, 16, v52
	v_and_b32_e32 v99, 0xffff0000, v52
	s_waitcnt vmcnt(1)
	v_lshlrev_b32_e32 v104, 16, v58
	v_and_b32_e32 v105, 0xffff0000, v58
	v_lshlrev_b32_e32 v96, 16, v50
	v_and_b32_e32 v97, 0xffff0000, v50
	v_lshlrev_b32_e32 v50, 16, v51
	v_and_b32_e32 v51, 0xffff0000, v51
	v_lshlrev_b32_e32 v52, 16, v53
	v_and_b32_e32 v53, 0xffff0000, v53
	v_lshlrev_b32_e32 v102, 16, v56
	v_and_b32_e32 v103, 0xffff0000, v56
	v_lshlrev_b32_e32 v56, 16, v57
	v_and_b32_e32 v57, 0xffff0000, v57
	s_waitcnt vmcnt(0)
	v_lshlrev_b32_e32 v106, 16, v60
	v_and_b32_e32 v107, 0xffff0000, v60
	v_lshlrev_b32_e32 v60, 16, v61
	v_and_b32_e32 v61, 0xffff0000, v61
	v_pk_add_f32 v[48:49], v[66:67], v[48:49]
	v_pk_add_f32 v[66:67], v[72:73], v[98:99]
	v_pk_add_f32 v[72:73], v[84:85], v[104:105]
	v_add_f32_e32 v84, 1.0, v128
	v_add_f32_e32 v85, 1.0, v129
	v_add_f32_e32 v98, 1.0, v136
	v_add_f32_e32 v99, 1.0, v137
	v_pk_add_f32 v[14:15], v[64:65], v[14:15]
	v_pk_add_f32 v[64:65], v[68:69], v[96:97]
	v_pk_add_f32 v[50:51], v[70:71], v[50:51]
	v_pk_add_f32 v[52:53], v[74:75], v[52:53]
	v_pk_add_f32 v[70:71], v[80:81], v[102:103]
	v_pk_add_f32 v[56:57], v[82:83], v[56:57]
	v_pk_add_f32 v[74:75], v[88:89], v[106:107]
	v_pk_add_f32 v[60:61], v[90:91], v[60:61]
	v_add_f32_e32 v82, 1.0, v126
	v_add_f32_e32 v83, 1.0, v127
	v_add_f32_e32 v88, 1.0, v130
	v_add_f32_e32 v89, 1.0, v131
	v_add_f32_e32 v90, 1.0, v132
	v_add_f32_e32 v91, 1.0, v133
	v_add_f32_e32 v96, 1.0, v134
	v_add_f32_e32 v97, 1.0, v135
	v_add_f32_e32 v102, 1.0, v138
	v_add_f32_e32 v103, 1.0, v139
	v_add_f32_e32 v112, 1.0, v112
	v_add_f32_e32 v113, 1.0, v113
	v_add_f32_e32 v126, 1.0, v114
	v_add_f32_e32 v127, 1.0, v115
	v_add_f32_e32 v130, 1.0, v118
	v_add_f32_e32 v131, 1.0, v119
	v_add_f32_e32 v132, 1.0, v120
	v_add_f32_e32 v133, 1.0, v121
	v_add_f32_e32 v134, 1.0, v122
	v_add_f32_e32 v135, 1.0, v123
	v_rcp_f32_e32 v84, v84
	v_rcp_f32_e32 v85, v85
	v_rcp_f32_e32 v98, v98
	v_rcp_f32_e32 v99, v99
	v_add_f32_e32 v128, 1.0, v116
	v_add_f32_e32 v129, 1.0, v117
	v_add_f32_e32 v136, 1.0, v124
	v_add_f32_e32 v137, 1.0, v125
	v_rcp_f32_e32 v88, v88
	v_rcp_f32_e32 v89, v89
	v_rcp_f32_e32 v102, v102
	v_rcp_f32_e32 v103, v103
	v_rcp_f32_e32 v112, v112
	v_rcp_f32_e32 v113, v113
	v_rcp_f32_e32 v116, v126
	v_rcp_f32_e32 v117, v127
	v_rcp_f32_e32 v124, v130
	v_rcp_f32_e32 v125, v131
	v_rcp_f32_e32 v126, v132
	v_rcp_f32_e32 v127, v133
	v_rcp_f32_e32 v130, v134
	v_rcp_f32_e32 v131, v135
	v_mul_f32_e32 v108, 0xbfb8aa3b, v20
	v_mul_f32_e32 v109, 0xbfb8aa3b, v21
	v_lshlrev_b32_e32 v100, 16, v54
	v_and_b32_e32 v101, 0xffff0000, v54
	v_lshlrev_b32_e32 v54, 16, v55
	v_and_b32_e32 v55, 0xffff0000, v55
	v_lshlrev_b32_e32 v58, 16, v59
	v_and_b32_e32 v59, 0xffff0000, v59
	v_rcp_f32_e32 v82, v82
	v_rcp_f32_e32 v83, v83
	v_rcp_f32_e32 v90, v90
	v_rcp_f32_e32 v91, v91
	v_exp_f32_e32 v140, v108
	v_exp_f32_e32 v141, v109
	v_lshlrev_b32_e32 v108, 16, v62
	v_and_b32_e32 v109, 0xffff0000, v62
	v_lshlrev_b32_e32 v62, 16, v63
	v_and_b32_e32 v63, 0xffff0000, v63
	v_pk_add_f32 v[68:69], v[76:77], v[100:101]
	v_pk_add_f32 v[54:55], v[78:79], v[54:55]
	v_pk_add_f32 v[58:59], v[86:87], v[58:59]
	v_cvt_pk_bf16_f32 v15, v14, v15
	v_cvt_pk_bf16_f32 v49, v48, v49
	v_cvt_pk_bf16_f32 v66, v66, v67
	v_cvt_pk_bf16_f32 v67, v52, v53
	v_pk_add_f32 v[76:77], v[92:93], v[108:109]
	v_pk_add_f32 v[62:63], v[94:95], v[62:63]
	v_cvt_pk_bf16_f32 v64, v64, v65
	v_cvt_pk_bf16_f32 v65, v50, v51
	v_cvt_pk_bf16_f32 v68, v68, v69
	v_cvt_pk_bf16_f32 v69, v54, v55
	v_cvt_pk_bf16_f32 v70, v70, v71
	v_cvt_pk_bf16_f32 v71, v56, v57
	v_cvt_pk_bf16_f32 v72, v72, v73
	v_cvt_pk_bf16_f32 v73, v58, v59
	v_cvt_pk_bf16_f32 v74, v74, v75
	v_cvt_pk_bf16_f32 v75, v60, v61
	v_lshlrev_b32_e32 v14, 16, v15
	v_and_b32_e32 v15, 0xffff0000, v15
	v_lshlrev_b32_e32 v48, 16, v49
	v_and_b32_e32 v49, 0xffff0000, v49
	v_and_b32_e32 v55, 0xffff0000, v66
	v_lshlrev_b32_e32 v56, 16, v67
	v_and_b32_e32 v57, 0xffff0000, v67
	v_pk_mul_f32 v[2:3], v[84:85], v[2:3]
	v_pk_mul_f32 v[10:11], v[98:99], v[10:11]
	v_cvt_pk_bf16_f32 v76, v76, v77
	v_cvt_pk_bf16_f32 v77, v62, v63
	v_lshlrev_b32_e32 v50, 16, v64
	v_and_b32_e32 v51, 0xffff0000, v64
	v_lshlrev_b32_e32 v52, 16, v65
	v_and_b32_e32 v53, 0xffff0000, v65
	v_lshlrev_b32_e32 v54, 16, v66
	v_lshlrev_b32_e32 v58, 16, v68
	v_and_b32_e32 v59, 0xffff0000, v68
	v_lshlrev_b32_e32 v60, 16, v69
	v_and_b32_e32 v61, 0xffff0000, v69
	v_lshlrev_b32_e32 v62, 16, v70
	v_and_b32_e32 v63, 0xffff0000, v70
	v_lshlrev_b32_e32 v64, 16, v71
	v_and_b32_e32 v65, 0xffff0000, v71
	v_lshlrev_b32_e32 v66, 16, v72
	v_and_b32_e32 v67, 0xffff0000, v72
	v_lshlrev_b32_e32 v68, 16, v73
	v_and_b32_e32 v69, 0xffff0000, v73
	v_lshlrev_b32_e32 v70, 16, v74
	v_and_b32_e32 v71, 0xffff0000, v74
	v_lshlrev_b32_e32 v72, 16, v75
	v_and_b32_e32 v73, 0xffff0000, v75
	v_mov_b32_e32 v87, v48
	v_mov_b32_e32 v101, v56
	v_pk_mul_f32 v[4:5], v[88:89], v[4:5]
	v_pk_mul_f32 v[24:25], v[102:103], v[24:25]
	v_pk_mul_f32 v[26:27], v[112:113], v[26:27]
	v_pk_mul_f32 v[28:29], v[116:117], v[28:29]
	v_pk_mul_f32 v[30:31], v[126:127], v[30:31]
	v_pk_mul_f32 v[40:41], v[130:131], v[40:41]
	v_pk_mul_f32 v[2:3], v[2:3], v[48:49]
	v_mov_b32_e32 v48, v15
	v_pk_mul_f32 v[10:11], v[10:11], v[56:57]
	v_mov_b32_e32 v56, v55
	v_lshlrev_b32_e32 v74, 16, v76
	v_and_b32_e32 v75, 0xffff0000, v76
	v_lshlrev_b32_e32 v76, 16, v77
	v_and_b32_e32 v77, 0xffff0000, v77
	v_mov_b32_e32 v80, v53
	v_mov_b32_e32 v81, v51
	v_mov_b32_e32 v86, v14
	v_mov_b32_e32 v94, v61
	v_mov_b32_e32 v95, v59
	v_mov_b32_e32 v100, v54
	v_mov_b32_e32 v115, v64
	v_rcp_f32_e32 v119, v129
	v_mov_b32_e32 v129, v72
	v_pk_mul_f32 v[0:1], v[82:83], v[0:1]
	v_pk_mul_f32 v[6:7], v[90:91], v[6:7]
	v_pk_mul_f32 v[4:5], v[4:5], v[14:15]
	v_pk_mul_f32 v[14:15], v[24:25], v[54:55]
	v_pk_mul_f32 v[24:25], v[26:27], v[64:65]
	v_mov_b32_e32 v64, v63
	v_pk_mul_f32 v[26:27], v[28:29], v[62:63]
	v_pk_mul_f32 v[28:29], v[30:31], v[72:73]
	v_mov_b32_e32 v72, v71
	v_pk_mul_f32 v[30:31], v[40:41], v[70:71]
	v_pk_mul_f32 v[40:41], v[48:49], v[48:49]
	v_pk_mul_f32 v[48:49], v[56:57], v[56:57]
	v_mov_b32_e32 v78, v52
	v_mov_b32_e32 v79, v50
	v_mov_b32_e32 v92, v60
	v_mov_b32_e32 v93, v58
	v_mov_b32_e32 v108, v69
	v_mov_b32_e32 v109, v67
	v_mov_b32_e32 v114, v62
	v_rcp_f32_e32 v118, v128
	v_mov_b32_e32 v122, v77
	v_mov_b32_e32 v123, v75
	v_mov_b32_e32 v128, v70
	v_pk_mul_f32 v[80:81], v[80:81], v[80:81]
	v_pk_mul_f32 v[94:95], v[94:95], v[94:95]
	v_pk_mul_f32 v[0:1], v[0:1], v[50:51]
	v_pk_mul_f32 v[6:7], v[6:7], v[52:53]
	v_pk_mul_f32 v[50:51], v[64:65], v[64:65]
	v_pk_mul_f32 v[52:53], v[72:73], v[72:73]
	v_pk_fma_f32 v[40:41], v[86:87], v[86:87], v[40:41]
	v_pk_fma_f32 v[48:49], v[100:101], v[100:101], v[48:49]
	v_mov_b32_e32 v106, v68
	v_mov_b32_e32 v107, v66
	v_mov_b32_e32 v120, v76
	v_mov_b32_e32 v121, v74
	v_pk_mul_f32 v[108:109], v[108:109], v[108:109]
	v_pk_mul_f32 v[122:123], v[122:123], v[122:123]
	v_pk_fma_f32 v[78:79], v[78:79], v[78:79], v[80:81]
	v_pk_fma_f32 v[80:81], v[92:93], v[92:93], v[94:95]
	v_pk_fma_f32 v[50:51], v[114:115], v[114:115], v[50:51]
	v_pk_fma_f32 v[52:53], v[128:129], v[128:129], v[52:53]
	v_mov_b32_e32 v54, v48
	v_mov_b32_e32 v55, v40
	v_mov_b32_e32 v40, v49
	v_pk_fma_f32 v[92:93], v[106:107], v[106:107], v[108:109]
	v_pk_fma_f32 v[94:95], v[120:121], v[120:121], v[122:123]
	v_mov_b32_e32 v106, v81
	v_mov_b32_e32 v107, v79
	v_mov_b32_e32 v48, v52
	v_mov_b32_e32 v49, v50
	v_mov_b32_e32 v50, v53
	v_pk_add_f32 v[40:41], v[54:55], v[40:41]
	v_mov_b32_e32 v81, v78
	v_mov_b32_e32 v78, v95
	v_mov_b32_e32 v79, v93
	v_pk_add_f32 v[48:49], v[48:49], v[50:51]
	v_pk_add_f32 v[40:41], v[106:107], v[40:41]
	v_mov_b32_e32 v95, v92
	v_pk_add_f32 v[48:49], v[78:79], v[48:49]
	v_pk_add_f32 v[40:41], v[80:81], v[40:41]
	v_pk_add_f32 v[48:49], v[94:95], v[48:49]
	ds_bpermute_b32 v51, v42, v41
	ds_bpermute_b32 v50, v42, v40
	ds_bpermute_b32 v53, v42, v49
	ds_bpermute_b32 v52, v42, v48
	v_mul_f32_e32 v110, 0xbfb8aa3b, v22
	v_mul_f32_e32 v111, 0xbfb8aa3b, v23
	s_waitcnt lgkmcnt(2)
	v_pk_add_f32 v[40:41], v[40:41], v[50:51]
	ds_bpermute_b32 v51, v43, v41
	s_waitcnt lgkmcnt(1)
	v_pk_add_f32 v[48:49], v[48:49], v[52:53]
	ds_bpermute_b32 v50, v43, v40
	ds_bpermute_b32 v53, v43, v49
	ds_bpermute_b32 v52, v43, v48
	v_exp_f32_e32 v110, v110
	v_exp_f32_e32 v111, v111
	s_waitcnt lgkmcnt(2)
	v_pk_add_f32 v[40:41], v[40:41], v[50:51]
	ds_bpermute_b32 v51, v44, v41
	s_waitcnt lgkmcnt(1)
	v_pk_add_f32 v[48:49], v[48:49], v[52:53]
	ds_bpermute_b32 v50, v44, v40
	ds_bpermute_b32 v53, v44, v49
	ds_bpermute_b32 v52, v44, v48
	v_add_f32_e32 v104, 1.0, v140
	v_add_f32_e32 v105, 1.0, v141
	s_waitcnt lgkmcnt(2)
	v_pk_add_f32 v[40:41], v[40:41], v[50:51]
	ds_bpermute_b32 v51, v45, v41
	s_waitcnt lgkmcnt(1)
	v_pk_add_f32 v[48:49], v[48:49], v[52:53]
	ds_bpermute_b32 v50, v45, v40
	ds_bpermute_b32 v53, v45, v49
	ds_bpermute_b32 v52, v45, v48
	v_add_f32_e32 v110, 1.0, v110
	v_add_f32_e32 v111, 1.0, v111
	s_waitcnt lgkmcnt(2)
	v_pk_add_f32 v[40:41], v[40:41], v[50:51]
	ds_bpermute_b32 v51, v46, v41
	s_waitcnt lgkmcnt(1)
	v_pk_add_f32 v[48:49], v[48:49], v[52:53]
	ds_bpermute_b32 v50, v46, v40
	ds_bpermute_b32 v53, v46, v49
	ds_bpermute_b32 v52, v46, v48
	v_rcp_f32_e32 v96, v96
	v_rcp_f32_e32 v97, v97
	s_waitcnt lgkmcnt(2)
	v_pk_add_f32 v[40:41], v[40:41], v[50:51]
	ds_bpermute_b32 v51, v47, v41
	s_waitcnt lgkmcnt(1)
	v_pk_add_f32 v[48:49], v[48:49], v[52:53]
	ds_bpermute_b32 v50, v47, v40
	ds_bpermute_b32 v53, v47, v49
	ds_bpermute_b32 v52, v47, v48
	v_rcp_f32_e32 v104, v104
	v_rcp_f32_e32 v105, v105
	s_waitcnt lgkmcnt(2)
	v_pk_add_f32 v[40:41], v[40:41], v[50:51]
	v_rcp_f32_e32 v110, v110
	s_waitcnt lgkmcnt(0)
	v_pk_add_f32 v[48:49], v[48:49], v[52:53]
	v_pk_fma_f32 v[40:41], v[40:41], s[18:19], v[34:35] op_sel_hi:[1,0,0]
	v_pk_fma_f32 v[48:49], v[48:49], s[18:19], v[34:35] op_sel_hi:[1,0,0]
	v_mul_f32_e32 v50, 0x4b800000, v41
	v_cmp_gt_f32_e64 s[12:13], s22, v41
	v_mul_f32_e32 v51, 0x4b800000, v40
	v_cmp_gt_f32_e32 vcc, s22, v40
	v_mul_f32_e32 v52, 0x4b800000, v49
	v_mul_f32_e32 v53, 0x4b800000, v48
	v_cmp_gt_f32_e64 s[6:7], s22, v48
	v_cmp_gt_f32_e64 s[10:11], s22, v49
	v_cndmask_b32_e64 v41, v41, v50, s[12:13]
	v_cndmask_b32_e32 v40, v40, v51, vcc
	v_cndmask_b32_e64 v49, v49, v52, s[10:11]
	v_cndmask_b32_e64 v48, v48, v53, s[6:7]
	v_rsq_f32_e32 v41, v41
	v_rcp_f32_e32 v111, v111
	v_rcp_f32_e32 v132, v136
	v_rcp_f32_e32 v133, v137
	v_rsq_f32_e32 v50, v40
	v_rsq_f32_e32 v49, v49
	v_rsq_f32_e32 v51, v48
	v_mul_f32_e32 v40, 0x45800000, v41
	v_pk_mul_f32 v[8:9], v[96:97], v[8:9]
	v_pk_mul_f32 v[20:21], v[104:105], v[20:21]
	v_pk_mul_f32 v[22:23], v[110:111], v[22:23]
	v_pk_mul_f32 v[16:17], v[118:119], v[16:17]
	v_pk_mul_f32 v[18:19], v[124:125], v[18:19]
	v_pk_mul_f32 v[12:13], v[132:133], v[12:13]
	v_mul_f32_e32 v48, 0x45800000, v50
	v_mul_f32_e32 v52, 0x45800000, v49
	v_mul_f32_e32 v53, 0x45800000, v51
	v_cndmask_b32_e64 v40, v41, v40, s[12:13]
	v_pk_mul_f32 v[8:9], v[8:9], v[58:59]
	v_pk_mul_f32 v[20:21], v[20:21], v[60:61]
	v_pk_mul_f32 v[22:23], v[22:23], v[66:67]
	v_pk_mul_f32 v[16:17], v[16:17], v[68:69]
	v_pk_mul_f32 v[18:19], v[18:19], v[74:75]
	v_pk_mul_f32 v[12:13], v[12:13], v[76:77]
	v_cndmask_b32_e32 v48, v50, v48, vcc
	v_cndmask_b32_e64 v50, v49, v52, s[10:11]
	v_cndmask_b32_e64 v52, v51, v53, s[6:7]
	v_pk_mul_f32 v[4:5], v[4:5], v[40:41] op_sel_hi:[1,0]
	v_pk_mul_f32 v[2:3], v[2:3], v[40:41] op_sel_hi:[1,0]
	v_pk_mul_f32 v[54:55], v[0:1], v[40:41] op_sel_hi:[1,0]
	v_pk_mul_f32 v[6:7], v[6:7], v[40:41] op_sel_hi:[1,0]
	v_pk_mul_f32 v[14:15], v[14:15], v[48:49] op_sel_hi:[1,0]
	v_pk_mul_f32 v[10:11], v[10:11], v[48:49] op_sel_hi:[1,0]
	v_pk_mul_f32 v[8:9], v[8:9], v[48:49] op_sel_hi:[1,0]
	v_pk_mul_f32 v[20:21], v[20:21], v[48:49] op_sel_hi:[1,0]
	v_pk_mul_f32 v[26:27], v[26:27], v[50:51] op_sel_hi:[1,0]
	v_pk_mul_f32 v[24:25], v[24:25], v[50:51] op_sel_hi:[1,0]
	v_pk_mul_f32 v[22:23], v[22:23], v[50:51] op_sel_hi:[1,0]
	v_pk_mul_f32 v[16:17], v[16:17], v[50:51] op_sel_hi:[1,0]
	v_pk_mul_f32 v[30:31], v[30:31], v[52:53] op_sel_hi:[1,0]
	v_pk_mul_f32 v[28:29], v[28:29], v[52:53] op_sel_hi:[1,0]
	v_pk_mul_f32 v[18:19], v[18:19], v[52:53] op_sel_hi:[1,0]
	v_pk_mul_f32 v[40:41], v[12:13], v[52:53] op_sel_hi:[1,0]
	v_cvt_pk_bf16_f32 v0, v4, v5
	v_cvt_pk_bf16_f32 v1, v2, v3
	v_cvt_pk_bf16_f32 v2, v54, v55
	v_cvt_pk_bf16_f32 v3, v6, v7
	v_cvt_pk_bf16_f32 v4, v14, v15
	v_cvt_pk_bf16_f32 v5, v10, v11
	v_cvt_pk_bf16_f32 v6, v8, v9
	v_cvt_pk_bf16_f32 v7, v20, v21
	v_cvt_pk_bf16_f32 v8, v26, v27
	v_cvt_pk_bf16_f32 v9, v24, v25
	v_cvt_pk_bf16_f32 v10, v22, v23
	v_cvt_pk_bf16_f32 v11, v16, v17
	v_cvt_pk_bf16_f32 v12, v30, v31
	v_cvt_pk_bf16_f32 v13, v28, v29
	v_cvt_pk_bf16_f32 v14, v18, v19
	v_cvt_pk_bf16_f32 v15, v40, v41
	global_store_dwordx4 v[38:39], v[0:3], off
	global_store_dwordx4 v[36:37], v[4:7], off offset:1024
	global_store_dwordx4 v[36:37], v[8:11], off offset:2048
	global_store_dwordx4 v[36:37], v[12:15], off offset:3072
	s_cbranch_scc1 .LBB0_406
